# v22: memKV K-path k-norm gains staged once in free LDS, blocks 1-7 read them with ds_read_b128 (no vmcnt store drains); w_in K-loop re-aligned
# baseline (speedup 1.0000x reference)
; __device__ __forceinline__ float quad_sum(float s) { s += __shfl_xor(s, 16); s += __shfl_xor(s, 32); return s; }
; __device__ __forceinline__ float sq4(const f32x4 a) { return (a[0] * a[0] + a[1] * a[1]) + (a[2] * a[2] + a[3] * a[3]); }
; __device__ __forceinline__ u32x4 pack8(const f32x4 a, const f32x4 b) { u32x4 w; w.x = cvt_pk_bf16(a[0], a[1]); w.y = cvt_pk_bf16(a[2], a[3]); w.z = cvt_pk_bf16(b[0], b[1]); w.w = cvt_pk_bf16(b[2], b[3]); return w; }
;     __device__ __forceinline__ void operator()(const f32x4 (&acc)[2][2][4][2], const Unit& u, int wr, int wc, int fr, int fq) const {
;     ...
;             bf16_t* MK = (bf16_t*)(ws + WS_MK); float* o_mk = out + O_MKP;
;             const float* g = (const float*)(ws + WS_GT) + l * 256 + 192;
; #pragma unroll
;             for (int ai = 0; ai < 2; ++ai)
; #pragma unroll
;                 for (int m = 0; m < 4; ++m) {
;                     int mrow = ai * HALF + wr * 64 + m * 16 + fr;
;                     asm volatile("" : "+v"(mrow));
;                     const float rs = MRS[b * 256 + mrow];
;                     f32x4 v[2][2];
; #pragma unroll
;                     for (int bj = 0; bj < 2; ++bj)
; #pragma unroll
;                         for (int n = 0; n < 2; ++n) v[bj][n] = acc[ai][bj][m][n] * rs;
;                     float ss = (sq4(v[0][0]) + sq4(v[0][1])) + (sq4(v[1][0]) + sq4(v[1][1]));
;                     ss = quad_sum(ss);
;                     const float hr = 1.0f / sqrtf(ss * (1.0f / 64.0f) + E_EPS);
; #pragma unroll
;                     for (int bj = 0; bj < 2; ++bj) {
;                         const int c0 = bj * 32 + 8 * fq;
;                         const f32x4 g0 = *(const f32x4*)(g + c0), g1 = *(const f32x4*)(g + c0 + 4);
;                         const f32x4 o0 = v[bj][0] * hr * g0, o1 = v[bj][1] * hr * g1;
;                         *(u32x4*)(MK + ((size_t)(l * 40 + b) * 256 + mrow) * 256 + wc * 64 + c0) = pack8(o0, o1);
.LBB0_516:
	s_lshl_b32 s0, s4, 8
	s_ashr_i32 s1, s0, 31
	s_lshl_b64 s[0:1], s[0:1], 2
	s_add_u32 s0, s48, s0
	s_addc_u32 s1, s49, s1
	s_add_u32 s40, s0, 0x8510300
	s_addc_u32 s41, s1, 0
	v_and_b32_e32 v155, 15, v222
	v_lshlrev_b32_e32 v155, 4, v155
	global_load_dwordx4 v[132:135], v155, s[40:41]
	s_lshl_b32 s2, s14, 8
	v_mov_b32_e32 v156, v145
	s_add_i32 s0, s5, s14
	v_add_u32_e32 v128, s2, v156
	v_ashrrev_i32_e32 v129, 31, v128
	v_lshl_add_u64 v[128:129], v[128:129], 2, s[20:21]
	global_load_dword v130, v[128:129], off
	v_add_u32_e32 v128, s2, v149
	v_ashrrev_i32_e32 v129, 31, v128
	v_lshl_add_u64 v[128:129], v[128:129], 2, s[20:21]
	global_load_dword v190, v[128:129], off
	v_add_u32_e32 v128, s2, v162
	v_ashrrev_i32_e32 v129, 31, v128
	v_lshl_add_u64 v[128:129], v[128:129], 2, s[20:21]
	global_load_dword v191, v[128:129], off
	v_add_u32_e32 v128, s2, v163
	v_ashrrev_i32_e32 v129, 31, v128
	v_lshl_add_u64 v[128:129], v[128:129], 2, s[20:21]
	global_load_dword v217, v[128:129], off
	v_add_u32_e32 v128, s2, v164
	v_ashrrev_i32_e32 v129, 31, v128
	v_lshl_add_u64 v[128:129], v[128:129], 2, s[20:21]
	global_load_dword v220, v[128:129], off
	v_add_u32_e32 v128, s2, v165
	v_ashrrev_i32_e32 v129, 31, v128
	v_lshl_add_u64 v[128:129], v[128:129], 2, s[20:21]
	global_load_dword v223, v[128:129], off
	v_add_u32_e32 v128, s2, v166
	v_ashrrev_i32_e32 v129, 31, v128
	v_lshl_add_u64 v[128:129], v[128:129], 2, s[20:21]
	global_load_dword v226, v[128:129], off
	v_add_u32_e32 v128, s2, v167
	v_ashrrev_i32_e32 v129, 31, v128
	v_lshl_add_u64 v[128:129], v[128:129], 2, s[20:21]
	global_load_dword v250, v[128:129], off
	s_mov_b32 s3, 0xf800000
	s_ashr_i32 s1, s0, 31
	s_lshl_b64 s[8:9], s[0:1], 17
	s_add_u32 s14, s47, s8
	s_addc_u32 s15, s93, s9
	s_lshl_b32 s1, s4, 5
	s_sub_i32 s0, s0, s1
	s_ashr_i32 s1, s0, 31
	s_lshl_b64 s[0:1], s[0:1], 18
	s_add_u32 s24, s94, s0
	s_addc_u32 s25, s95, s1
	v_ashrrev_i32_e32 v157, 31, v156
	v_lshlrev_b32_e32 v184, 2, v144
	s_waitcnt vmcnt(0)
	v_add_u32_e32 v155, 0x20800, v155
	ds_write_b128 v155, v[132:135]
	s_nop 1
	v_pk_mul_f32 v[124:125], v[124:125], v[130:131] op_sel_hi:[1,0]
	v_pk_mul_f32 v[132:133], v[116:117], v[130:131] op_sel_hi:[1,0]
	v_pk_mul_f32 v[160:161], v[126:127], v[130:131] op_sel_hi:[1,0]
	v_pk_mul_f32 v[128:129], v[118:119], v[130:131] op_sel_hi:[1,0]
	v_pk_mul_f32 v[126:127], v[114:115], v[130:131] op_sel_hi:[1,0]
	v_mov_b32_e32 v114, v125
	v_mov_b32_e32 v115, v133
	v_pk_mul_f32 v[122:123], v[122:123], v[130:131] op_sel_hi:[1,0]
	v_pk_mul_f32 v[120:121], v[120:121], v[130:131] op_sel_hi:[1,0]
	v_pk_mul_f32 v[130:131], v[112:113], v[130:131] op_sel_hi:[1,0]
	v_mov_b32_e32 v112, v124
	v_mov_b32_e32 v113, v132
	v_pk_mul_f32 v[114:115], v[114:115], v[114:115]
	v_mov_b32_e32 v116, v161
	v_mov_b32_e32 v117, v129
	v_pk_fma_f32 v[112:113], v[112:113], v[112:113], v[114:115]
	v_mov_b32_e32 v114, v160
	v_mov_b32_e32 v115, v128
	v_pk_mul_f32 v[116:117], v[116:117], v[116:117]
	v_mov_b32_e32 v118, v123
	v_pk_fma_f32 v[114:115], v[114:115], v[114:115], v[116:117]
	v_mov_b32_e32 v116, v121
	v_mov_b32_e32 v117, v131
	v_pk_add_f32 v[112:113], v[112:113], v[114:115]
	v_mov_b32_e32 v114, v120
	v_mov_b32_e32 v115, v130
	v_pk_mul_f32 v[116:117], v[116:117], v[116:117]
	v_mov_b32_e32 v119, v127
	v_pk_fma_f32 v[114:115], v[114:115], v[114:115], v[116:117]
	v_mov_b32_e32 v116, v122
	v_mov_b32_e32 v117, v126
	v_pk_mul_f32 v[118:119], v[118:119], v[118:119]
	s_nop 0
	v_pk_fma_f32 v[116:117], v[116:117], v[116:117], v[118:119]
	s_nop 0
	v_pk_add_f32 v[114:115], v[114:115], v[116:117]
	s_nop 0
	v_pk_add_f32 v[112:113], v[112:113], v[114:115]
	v_and_b32_e32 v114, 64, v222
	v_add_f32_e32 v112, v112, v113
	v_xor_b32_e32 v113, 16, v222
	v_add_u32_e32 v114, 64, v114
	v_cmp_lt_i32_e32 vcc, v113, v114
	s_nop 1
	v_cndmask_b32_e32 v113, v222, v113, vcc
	v_lshlrev_b32_e32 v135, 2, v113
	ds_bpermute_b32 v113, v135, v112
	s_waitcnt lgkmcnt(0)
	v_add_f32_e32 v112, v112, v113
	v_xor_b32_e32 v113, 32, v222
	v_cmp_lt_i32_e32 vcc, v113, v114
	s_nop 1
	v_cndmask_b32_e32 v113, v222, v113, vcc
	v_lshlrev_b32_e32 v155, 2, v113
	ds_bpermute_b32 v113, v155, v112
	s_waitcnt lgkmcnt(0)
	v_add_f32_e32 v112, v112, v113
	v_fmamk_f32 v112, v112, 0x3c800000, v218
	v_cmp_gt_f32_e32 vcc, s3, v112
	v_mul_f32_e32 v113, 0x4f800000, v112
	s_nop 0
	v_cndmask_b32_e32 v112, v112, v113, vcc
	v_sqrt_f32_e32 v113, v112
	s_nop 0
	v_add_u32_e32 v114, -1, v113
	v_fma_f32 v115, -v114, v113, v112
	v_cmp_ge_f32_e64 s[0:1], 0, v115
	v_add_u32_e32 v115, 1, v113
	s_nop 0
	v_cndmask_b32_e64 v114, v113, v114, s[0:1]
	v_fma_f32 v113, -v115, v113, v112
	v_cmp_lt_f32_e64 s[0:1], 0, v113
	s_nop 1
	v_cndmask_b32_e64 v113, v114, v115, s[0:1]
	v_mul_f32_e32 v114, 0x37800000, v113
	v_cndmask_b32_e32 v113, v113, v114, vcc
	v_cmp_class_f32_e32 vcc, v112, v219
	s_nop 1
	v_cndmask_b32_e32 v112, v113, v112, vcc
	v_div_scale_f32 v113, s[0:1], v112, v112, 1.0
	v_rcp_f32_e32 v114, v113
	s_nop 0
	v_fma_f32 v115, -v113, v114, 1.0
	v_fmac_f32_e32 v114, v115, v114
	v_div_scale_f32 v115, vcc, 1.0, v112, 1.0
	v_mul_f32_e32 v116, v115, v114
	v_fma_f32 v117, -v113, v116, v115
	v_fmac_f32_e32 v116, v117, v114
	v_fma_f32 v113, -v113, v116, v115
	v_div_fmas_f32 v113, v113, v114, v116
	v_div_fixup_f32 v134, v113, v112, 1.0
	v_lshlrev_b64 v[112:113], 9, v[156:157]
	v_lshl_add_u64 v[158:159], s[14:15], 0, v[112:113]
	v_lshlrev_b64 v[112:113], 10, v[156:157]
	v_lshl_add_u64 v[156:157], s[24:25], 0, v[112:113]
	global_load_dwordx4 v[112:115], v184, s[40:41] offset:16
	global_load_dwordx4 v[116:119], v184, s[40:41]
	v_pk_mul_f32 v[124:125], v[124:125], v[134:135] op_sel_hi:[1,0]
	v_pk_mul_f32 v[160:161], v[160:161], v[134:135] op_sel_hi:[1,0]
	v_pk_mul_f32 v[120:121], v[120:121], v[134:135] op_sel_hi:[1,0]
	v_pk_mul_f32 v[122:123], v[122:123], v[134:135] op_sel_hi:[1,0]
	v_lshl_add_u64 v[156:157], v[156:157], 0, v[184:185]
	s_waitcnt vmcnt(1)
; __device__ __forceinline__ float quad_sum(float s) { s += __shfl_xor(s, 16); s += __shfl_xor(s, 32); return s; }
; __device__ __forceinline__ float sq4(const f32x4 a) { return (a[0] * a[0] + a[1] * a[1]) + (a[2] * a[2] + a[3] * a[3]); }
; __device__ __forceinline__ u32x4 pack8(const f32x4 a, const f32x4 b) { u32x4 w; w.x = cvt_pk_bf16(a[0], a[1]); w.y = cvt_pk_bf16(a[2], a[3]); w.z = cvt_pk_bf16(b[0], b[1]); w.w = cvt_pk_bf16(b[2], b[3]); return w; }
;     __device__ __forceinline__ void operator()(const f32x4 (&acc)[2][2][4][2], const Unit& u, int wr, int wc, int fr, int fq) const {
;     ...
;                     int mrow = ai * HALF + wr * 64 + m * 16 + fr;
;                     asm volatile("" : "+v"(mrow));
;                     const float rs = MRS[b * 256 + mrow];
;                     f32x4 v[2][2];
; #pragma unroll
;                     for (int bj = 0; bj < 2; ++bj)
; #pragma unroll
;                         for (int n = 0; n < 2; ++n) v[bj][n] = acc[ai][bj][m][n] * rs;
;                     float ss = (sq4(v[0][0]) + sq4(v[0][1])) + (sq4(v[1][0]) + sq4(v[1][1]));
;                     ss = quad_sum(ss);
;                     const float hr = 1.0f / sqrtf(ss * (1.0f / 64.0f) + E_EPS);
; #pragma unroll
;                     for (int bj = 0; bj < 2; ++bj) {
;                         const int c0 = bj * 32 + 8 * fq;
;                         const f32x4 g0 = *(const f32x4*)(g + c0), g1 = *(const f32x4*)(g + c0 + 4);
;                         const f32x4 o0 = v[bj][0] * hr * g0, o1 = v[bj][1] * hr * g1;
;                         *(u32x4*)(MK + ((size_t)(l * 40 + b) * 256 + mrow) * 256 + wc * 64 + c0) = pack8(o0, o1);
;                         float* d = o_mk + ((size_t)(l * 8 + b) * 256 + mrow) * 256 + wc * 64 + c0; __builtin_nontemporal_store(o0, (f32x4*)d); __builtin_nontemporal_store(o1, (f32x4*)(d + 4));
;                     }
	v_pk_mul_f32 v[114:115], v[114:115], v[122:123]
	s_waitcnt vmcnt(0)
	v_pk_mul_f32 v[116:117], v[116:117], v[124:125]
	v_lshlrev_b32_e32 v124, 1, v144
	v_mov_b32_e32 v125, v185
	v_pk_mul_f32 v[118:119], v[118:119], v[160:161]
	v_lshl_add_u64 v[158:159], v[158:159], 0, v[124:125]
	v_pk_mul_f32 v[112:113], v[112:113], v[120:121]
	v_cvt_pk_bf16_f32 v120, v116, v117
	v_cvt_pk_bf16_f32 v121, v118, v119
	s_nop 0
	v_cvt_pk_bf16_f32 v122, v112, v113
	v_cvt_pk_bf16_f32 v123, v114, v115
	global_store_dwordx4 v[158:159], v[120:123], off
	global_store_dwordx4 v[156:157], v[116:119], off nt
	global_store_dwordx4 v[156:157], v[112:115], off offset:16 nt
	global_load_dwordx4 v[112:115], v169, s[40:41] offset:16
	s_nop 0
	global_load_dwordx4 v[116:119], v169, s[40:41]
	v_pk_mul_f32 v[120:121], v[132:133], v[134:135] op_sel_hi:[1,0]
	v_add_u32_e32 v132, 0x20800, v184
	v_pk_mul_f32 v[122:123], v[128:129], v[134:135] op_sel_hi:[1,0]
	s_waitcnt vmcnt(0)
	v_pk_mul_f32 v[116:117], v[116:117], v[120:121]
	v_pk_mul_f32 v[118:119], v[118:119], v[122:123]
	v_pk_mul_f32 v[120:121], v[130:131], v[134:135] op_sel_hi:[1,0]
	v_pk_mul_f32 v[122:123], v[126:127], v[134:135] op_sel_hi:[1,0]
	v_pk_mul_f32 v[112:113], v[112:113], v[120:121]
	v_pk_mul_f32 v[114:115], v[114:115], v[122:123]
	v_cvt_pk_bf16_f32 v120, v116, v117
	v_cvt_pk_bf16_f32 v121, v118, v119
	v_cvt_pk_bf16_f32 v122, v112, v113
	s_nop 0
	v_cvt_pk_bf16_f32 v123, v114, v115
	global_store_dwordx4 v[158:159], v[120:123], off offset:64
	global_store_dwordx4 v[156:157], v[116:119], off offset:128 nt
	global_store_dwordx4 v[156:157], v[112:115], off offset:144 nt
	s_nop 0
	v_mov_b32_e32 v118, v149
	s_nop 0
	v_mov_b32_e32 v112, v190
	v_ashrrev_i32_e32 v119, 31, v118
	v_pk_mul_f32 v[126:127], v[108:109], v[112:113] op_sel_hi:[1,0]
	v_pk_mul_f32 v[114:115], v[100:101], v[112:113] op_sel_hi:[1,0]
	v_pk_mul_f32 v[122:123], v[110:111], v[112:113] op_sel_hi:[1,0]
	v_pk_mul_f32 v[110:111], v[102:103], v[112:113] op_sel_hi:[1,0]
	v_pk_mul_f32 v[108:109], v[98:99], v[112:113] op_sel_hi:[1,0]
	v_mov_b32_e32 v98, v127
	v_mov_b32_e32 v99, v115
	v_pk_mul_f32 v[106:107], v[106:107], v[112:113] op_sel_hi:[1,0]
	v_pk_mul_f32 v[104:105], v[104:105], v[112:113] op_sel_hi:[1,0]
	v_pk_mul_f32 v[112:113], v[96:97], v[112:113] op_sel_hi:[1,0]
	v_mov_b32_e32 v96, v126
	v_mov_b32_e32 v97, v114
	v_pk_mul_f32 v[98:99], v[98:99], v[98:99]
	v_mov_b32_e32 v100, v123
	v_mov_b32_e32 v101, v111
	v_pk_fma_f32 v[96:97], v[96:97], v[96:97], v[98:99]
	v_mov_b32_e32 v98, v122
	v_mov_b32_e32 v99, v110
	v_pk_mul_f32 v[100:101], v[100:101], v[100:101]
	v_mov_b32_e32 v102, v107
	v_pk_fma_f32 v[98:99], v[98:99], v[98:99], v[100:101]
	v_mov_b32_e32 v100, v105
	v_mov_b32_e32 v101, v113
	v_pk_add_f32 v[96:97], v[96:97], v[98:99]
	v_mov_b32_e32 v98, v104
	v_mov_b32_e32 v99, v112
	v_pk_mul_f32 v[100:101], v[100:101], v[100:101]
	v_mov_b32_e32 v103, v109
	v_pk_fma_f32 v[98:99], v[98:99], v[98:99], v[100:101]
	v_mov_b32_e32 v100, v106
	v_mov_b32_e32 v101, v108
	v_pk_mul_f32 v[102:103], v[102:103], v[102:103]
	s_nop 0
	v_pk_fma_f32 v[100:101], v[100:101], v[100:101], v[102:103]
	s_nop 0
	v_pk_add_f32 v[98:99], v[98:99], v[100:101]
	s_nop 0
	v_pk_add_f32 v[96:97], v[96:97], v[98:99]
	s_nop 0
	v_add_f32_e32 v96, v96, v97
	ds_bpermute_b32 v97, v135, v96
	s_waitcnt lgkmcnt(0)
	v_add_f32_e32 v96, v96, v97
	ds_bpermute_b32 v97, v155, v96
	s_waitcnt lgkmcnt(0)
	v_add_f32_e32 v96, v96, v97
	v_fmamk_f32 v96, v96, 0x3c800000, v218
	v_cmp_gt_f32_e32 vcc, s3, v96
	v_mul_f32_e32 v97, 0x4f800000, v96
	s_nop 0
	v_cndmask_b32_e32 v96, v96, v97, vcc
	v_sqrt_f32_e32 v97, v96
	s_nop 0
	v_add_u32_e32 v98, -1, v97
	v_fma_f32 v99, -v98, v97, v96
	v_cmp_ge_f32_e64 s[0:1], 0, v99
	v_add_u32_e32 v99, 1, v97
	s_nop 0
	v_cndmask_b32_e64 v98, v97, v98, s[0:1]
	v_fma_f32 v97, -v99, v97, v96
	v_cmp_lt_f32_e64 s[0:1], 0, v97
	s_nop 1
	v_cndmask_b32_e64 v97, v98, v99, s[0:1]
	v_mul_f32_e32 v98, 0x37800000, v97
	v_cndmask_b32_e32 v97, v97, v98, vcc
	v_cmp_class_f32_e32 vcc, v96, v219
	s_nop 1
	v_cndmask_b32_e32 v96, v97, v96, vcc
	v_div_scale_f32 v97, s[0:1], v96, v96, 1.0
	v_rcp_f32_e32 v98, v97
	s_nop 0
	v_fma_f32 v99, -v97, v98, 1.0
	v_fmac_f32_e32 v98, v99, v98
	v_div_scale_f32 v99, vcc, 1.0, v96, 1.0
	v_mul_f32_e32 v100, v99, v98
	v_fma_f32 v101, -v97, v100, v99
	v_fmac_f32_e32 v100, v101, v98
	v_fma_f32 v97, -v97, v100, v99
	v_div_fmas_f32 v97, v97, v98, v100
	v_div_fixup_f32 v116, v97, v96, 1.0
	v_lshlrev_b64 v[96:97], 9, v[118:119]
	v_lshl_add_u64 v[120:121], s[14:15], 0, v[96:97]
	v_lshlrev_b64 v[96:97], 10, v[118:119]
	v_lshl_add_u64 v[118:119], s[24:25], 0, v[96:97]
	ds_read_b128 v[96:99], v132 offset:16
	ds_read_b128 v[100:103], v132
	v_pk_mul_f32 v[126:127], v[126:127], v[116:117] op_sel_hi:[1,0]
	v_pk_mul_f32 v[122:123], v[122:123], v[116:117] op_sel_hi:[1,0]
	v_pk_mul_f32 v[104:105], v[104:105], v[116:117] op_sel_hi:[1,0]
	v_pk_mul_f32 v[106:107], v[106:107], v[116:117] op_sel_hi:[1,0]
	v_lshl_add_u64 v[120:121], v[120:121], 0, v[124:125]
	v_lshl_add_u64 v[118:119], v[118:119], 0, v[184:185]
	s_waitcnt lgkmcnt(1)
	v_pk_mul_f32 v[98:99], v[98:99], v[106:107]
	s_waitcnt lgkmcnt(0)
	v_pk_mul_f32 v[102:103], v[102:103], v[122:123]
	v_pk_mul_f32 v[100:101], v[100:101], v[126:127]
	v_pk_mul_f32 v[96:97], v[96:97], v[104:105]
	v_cvt_pk_bf16_f32 v104, v100, v101
	v_cvt_pk_bf16_f32 v105, v102, v103
	s_nop 0
	v_cvt_pk_bf16_f32 v106, v96, v97
	v_cvt_pk_bf16_f32 v107, v98, v99
	global_store_dwordx4 v[120:121], v[104:107], off
	global_store_dwordx4 v[118:119], v[100:103], off nt
	global_store_dwordx4 v[118:119], v[96:99], off offset:16 nt
	ds_read_b128 v[96:99], v132 offset:144
	s_nop 0
	ds_read_b128 v[100:103], v132 offset:128
	v_pk_mul_f32 v[104:105], v[114:115], v[116:117] op_sel_hi:[1,0]
	v_pk_mul_f32 v[106:107], v[110:111], v[116:117] op_sel_hi:[1,0]
	s_waitcnt lgkmcnt(0)
; __device__ __forceinline__ float quad_sum(float s) { s += __shfl_xor(s, 16); s += __shfl_xor(s, 32); return s; }
; __device__ __forceinline__ float sq4(const f32x4 a) { return (a[0] * a[0] + a[1] * a[1]) + (a[2] * a[2] + a[3] * a[3]); }
; __device__ __forceinline__ u32x4 pack8(const f32x4 a, const f32x4 b) { u32x4 w; w.x = cvt_pk_bf16(a[0], a[1]); w.y = cvt_pk_bf16(a[2], a[3]); w.z = cvt_pk_bf16(b[0], b[1]); w.w = cvt_pk_bf16(b[2], b[3]); return w; }
;     __device__ __forceinline__ void operator()(const f32x4 (&acc)[2][2][4][2], const Unit& u, int wr, int wc, int fr, int fq) const {
;     ...
;                     int mrow = ai * HALF + wr * 64 + m * 16 + fr;
;                     asm volatile("" : "+v"(mrow));
;                     const float rs = MRS[b * 256 + mrow];
;                     f32x4 v[2][2];
; #pragma unroll
;                     for (int bj = 0; bj < 2; ++bj)
; #pragma unroll
;                         for (int n = 0; n < 2; ++n) v[bj][n] = acc[ai][bj][m][n] * rs;
;                     float ss = (sq4(v[0][0]) + sq4(v[0][1])) + (sq4(v[1][0]) + sq4(v[1][1]));
;                     ss = quad_sum(ss);
;                     const float hr = 1.0f / sqrtf(ss * (1.0f / 64.0f) + E_EPS);
; #pragma unroll
;                     for (int bj = 0; bj < 2; ++bj) {
;                         const int c0 = bj * 32 + 8 * fq;
;                         const f32x4 g0 = *(const f32x4*)(g + c0), g1 = *(const f32x4*)(g + c0 + 4);
;                         const f32x4 o0 = v[bj][0] * hr * g0, o1 = v[bj][1] * hr * g1;
;                         *(u32x4*)(MK + ((size_t)(l * 40 + b) * 256 + mrow) * 256 + wc * 64 + c0) = pack8(o0, o1);
;                         float* d = o_mk + ((size_t)(l * 8 + b) * 256 + mrow) * 256 + wc * 64 + c0; __builtin_nontemporal_store(o0, (f32x4*)d); __builtin_nontemporal_store(o1, (f32x4*)(d + 4));
;                     }
	v_pk_mul_f32 v[100:101], v[100:101], v[104:105]
	v_pk_mul_f32 v[102:103], v[102:103], v[106:107]
	v_pk_mul_f32 v[104:105], v[112:113], v[116:117] op_sel_hi:[1,0]
	v_pk_mul_f32 v[106:107], v[108:109], v[116:117] op_sel_hi:[1,0]
	v_pk_mul_f32 v[96:97], v[96:97], v[104:105]
	v_pk_mul_f32 v[98:99], v[98:99], v[106:107]
	v_cvt_pk_bf16_f32 v104, v100, v101
	v_cvt_pk_bf16_f32 v105, v102, v103
	v_cvt_pk_bf16_f32 v106, v96, v97
	s_nop 0
	v_cvt_pk_bf16_f32 v107, v98, v99
	global_store_dwordx4 v[120:121], v[104:107], off offset:64
	global_store_dwordx4 v[118:119], v[100:103], off offset:128 nt
	global_store_dwordx4 v[118:119], v[96:99], off offset:144 nt
	s_nop 0
	v_mov_b32_e32 v102, v162
	s_nop 0
	v_mov_b32_e32 v96, v191
	v_ashrrev_i32_e32 v103, 31, v102
	v_pk_mul_f32 v[108:109], v[92:93], v[96:97] op_sel_hi:[1,0]
	v_pk_mul_f32 v[98:99], v[84:85], v[96:97] op_sel_hi:[1,0]
	v_pk_mul_f32 v[106:107], v[94:95], v[96:97] op_sel_hi:[1,0]
	v_pk_mul_f32 v[94:95], v[86:87], v[96:97] op_sel_hi:[1,0]
	v_pk_mul_f32 v[92:93], v[82:83], v[96:97] op_sel_hi:[1,0]
	v_mov_b32_e32 v82, v109
	v_mov_b32_e32 v83, v99
	v_pk_mul_f32 v[90:91], v[90:91], v[96:97] op_sel_hi:[1,0]
	v_pk_mul_f32 v[88:89], v[88:89], v[96:97] op_sel_hi:[1,0]
	v_pk_mul_f32 v[96:97], v[80:81], v[96:97] op_sel_hi:[1,0]
	v_mov_b32_e32 v80, v108
	v_mov_b32_e32 v81, v98
	v_pk_mul_f32 v[82:83], v[82:83], v[82:83]
	v_mov_b32_e32 v84, v107
	v_mov_b32_e32 v85, v95
	v_pk_fma_f32 v[80:81], v[80:81], v[80:81], v[82:83]
	v_mov_b32_e32 v82, v106
	v_mov_b32_e32 v83, v94
	v_pk_mul_f32 v[84:85], v[84:85], v[84:85]
	v_mov_b32_e32 v86, v91
	v_pk_fma_f32 v[82:83], v[82:83], v[82:83], v[84:85]
	v_mov_b32_e32 v84, v89
	v_mov_b32_e32 v85, v97
	v_pk_add_f32 v[80:81], v[80:81], v[82:83]
	v_mov_b32_e32 v82, v88
	v_mov_b32_e32 v83, v96
	v_pk_mul_f32 v[84:85], v[84:85], v[84:85]
	v_mov_b32_e32 v87, v93
	v_pk_fma_f32 v[82:83], v[82:83], v[82:83], v[84:85]
	v_mov_b32_e32 v84, v90
	v_mov_b32_e32 v85, v92
	v_pk_mul_f32 v[86:87], v[86:87], v[86:87]
	s_nop 0
	v_pk_fma_f32 v[84:85], v[84:85], v[84:85], v[86:87]
	s_nop 0
	v_pk_add_f32 v[82:83], v[82:83], v[84:85]
	s_nop 0
	v_pk_add_f32 v[80:81], v[80:81], v[82:83]
	s_nop 0
	v_add_f32_e32 v80, v80, v81
	ds_bpermute_b32 v81, v135, v80
	s_waitcnt lgkmcnt(0)
	v_add_f32_e32 v80, v80, v81
	ds_bpermute_b32 v81, v155, v80
	s_waitcnt lgkmcnt(0)
	v_add_f32_e32 v80, v80, v81
	v_fmamk_f32 v80, v80, 0x3c800000, v218
	v_cmp_gt_f32_e32 vcc, s3, v80
	v_mul_f32_e32 v81, 0x4f800000, v80
	s_nop 0
	v_cndmask_b32_e32 v80, v80, v81, vcc
	v_sqrt_f32_e32 v81, v80
	s_nop 0
	v_add_u32_e32 v82, -1, v81
	v_fma_f32 v83, -v82, v81, v80
	v_cmp_ge_f32_e64 s[0:1], 0, v83
	v_add_u32_e32 v83, 1, v81
	s_nop 0
	v_cndmask_b32_e64 v82, v81, v82, s[0:1]
	v_fma_f32 v81, -v83, v81, v80
	v_cmp_lt_f32_e64 s[0:1], 0, v81
	s_nop 1
	v_cndmask_b32_e64 v81, v82, v83, s[0:1]
	v_mul_f32_e32 v82, 0x37800000, v81
	v_cndmask_b32_e32 v81, v81, v82, vcc
	v_cmp_class_f32_e32 vcc, v80, v219
	s_nop 1
	v_cndmask_b32_e32 v80, v81, v80, vcc
	v_div_scale_f32 v81, s[0:1], v80, v80, 1.0
	v_rcp_f32_e32 v82, v81
	s_nop 0
	v_fma_f32 v83, -v81, v82, 1.0
	v_fmac_f32_e32 v82, v83, v82
	v_div_scale_f32 v83, vcc, 1.0, v80, 1.0
	v_mul_f32_e32 v84, v83, v82
	v_fma_f32 v85, -v81, v84, v83
	v_fmac_f32_e32 v84, v85, v82
	v_fma_f32 v81, -v81, v84, v83
	v_div_fmas_f32 v81, v81, v82, v84
	v_div_fixup_f32 v100, v81, v80, 1.0
	v_lshlrev_b64 v[80:81], 9, v[102:103]
	v_lshl_add_u64 v[104:105], s[14:15], 0, v[80:81]
	v_lshlrev_b64 v[80:81], 10, v[102:103]
	v_lshl_add_u64 v[102:103], s[24:25], 0, v[80:81]
	ds_read_b128 v[80:83], v132 offset:16
	ds_read_b128 v[84:87], v132
	v_pk_mul_f32 v[108:109], v[108:109], v[100:101] op_sel_hi:[1,0]
	v_pk_mul_f32 v[106:107], v[106:107], v[100:101] op_sel_hi:[1,0]
	v_pk_mul_f32 v[88:89], v[88:89], v[100:101] op_sel_hi:[1,0]
	v_pk_mul_f32 v[90:91], v[90:91], v[100:101] op_sel_hi:[1,0]
	v_lshl_add_u64 v[104:105], v[104:105], 0, v[124:125]
	v_lshl_add_u64 v[102:103], v[102:103], 0, v[184:185]
	s_waitcnt lgkmcnt(1)
	v_pk_mul_f32 v[82:83], v[82:83], v[90:91]
	s_waitcnt lgkmcnt(0)
	v_pk_mul_f32 v[86:87], v[86:87], v[106:107]
	v_pk_mul_f32 v[84:85], v[84:85], v[108:109]
	v_pk_mul_f32 v[80:81], v[80:81], v[88:89]
	v_cvt_pk_bf16_f32 v88, v84, v85
	v_cvt_pk_bf16_f32 v89, v86, v87
	s_nop 0
	v_cvt_pk_bf16_f32 v90, v80, v81
	v_cvt_pk_bf16_f32 v91, v82, v83
	global_store_dwordx4 v[104:105], v[88:91], off
	global_store_dwordx4 v[102:103], v[84:87], off nt
	global_store_dwordx4 v[102:103], v[80:83], off offset:16 nt
	ds_read_b128 v[80:83], v132 offset:144
	s_nop 0
	ds_read_b128 v[84:87], v132 offset:128
	v_pk_mul_f32 v[88:89], v[98:99], v[100:101] op_sel_hi:[1,0]
	v_pk_mul_f32 v[90:91], v[94:95], v[100:101] op_sel_hi:[1,0]
	s_waitcnt lgkmcnt(0)
; __device__ __forceinline__ float quad_sum(float s) { s += __shfl_xor(s, 16); s += __shfl_xor(s, 32); return s; }
; __device__ __forceinline__ float sq4(const f32x4 a) { return (a[0] * a[0] + a[1] * a[1]) + (a[2] * a[2] + a[3] * a[3]); }
; __device__ __forceinline__ u32x4 pack8(const f32x4 a, const f32x4 b) { u32x4 w; w.x = cvt_pk_bf16(a[0], a[1]); w.y = cvt_pk_bf16(a[2], a[3]); w.z = cvt_pk_bf16(b[0], b[1]); w.w = cvt_pk_bf16(b[2], b[3]); return w; }
;     __device__ __forceinline__ void operator()(const f32x4 (&acc)[2][2][4][2], const Unit& u, int wr, int wc, int fr, int fq) const {
;     ...
;                     int mrow = ai * HALF + wr * 64 + m * 16 + fr;
;                     asm volatile("" : "+v"(mrow));
;                     const float rs = MRS[b * 256 + mrow];
;                     f32x4 v[2][2];
; #pragma unroll
;                     for (int bj = 0; bj < 2; ++bj)
; #pragma unroll
;                         for (int n = 0; n < 2; ++n) v[bj][n] = acc[ai][bj][m][n] * rs;
;                     float ss = (sq4(v[0][0]) + sq4(v[0][1])) + (sq4(v[1][0]) + sq4(v[1][1]));
;                     ss = quad_sum(ss);
;                     const float hr = 1.0f / sqrtf(ss * (1.0f / 64.0f) + E_EPS);
; #pragma unroll
;                     for (int bj = 0; bj < 2; ++bj) {
;                         const int c0 = bj * 32 + 8 * fq;
;                         const f32x4 g0 = *(const f32x4*)(g + c0), g1 = *(const f32x4*)(g + c0 + 4);
;                         const f32x4 o0 = v[bj][0] * hr * g0, o1 = v[bj][1] * hr * g1;
;                         *(u32x4*)(MK + ((size_t)(l * 40 + b) * 256 + mrow) * 256 + wc * 64 + c0) = pack8(o0, o1);
;                         float* d = o_mk + ((size_t)(l * 8 + b) * 256 + mrow) * 256 + wc * 64 + c0; __builtin_nontemporal_store(o0, (f32x4*)d); __builtin_nontemporal_store(o1, (f32x4*)(d + 4));
;                     }
	v_pk_mul_f32 v[84:85], v[84:85], v[88:89]
	v_pk_mul_f32 v[86:87], v[86:87], v[90:91]
	v_pk_mul_f32 v[88:89], v[96:97], v[100:101] op_sel_hi:[1,0]
	v_pk_mul_f32 v[90:91], v[92:93], v[100:101] op_sel_hi:[1,0]
	v_pk_mul_f32 v[80:81], v[80:81], v[88:89]
	v_pk_mul_f32 v[82:83], v[82:83], v[90:91]
	v_cvt_pk_bf16_f32 v88, v84, v85
	v_cvt_pk_bf16_f32 v89, v86, v87
	v_cvt_pk_bf16_f32 v90, v80, v81
	s_nop 0
	v_cvt_pk_bf16_f32 v91, v82, v83
	global_store_dwordx4 v[104:105], v[88:91], off offset:64
	global_store_dwordx4 v[102:103], v[84:87], off offset:128 nt
	global_store_dwordx4 v[102:103], v[80:83], off offset:144 nt
	s_nop 0
	v_mov_b32_e32 v86, v163
	s_nop 0
	v_mov_b32_e32 v80, v217
	v_ashrrev_i32_e32 v87, 31, v86
	v_pk_mul_f32 v[92:93], v[76:77], v[80:81] op_sel_hi:[1,0]
	v_pk_mul_f32 v[82:83], v[68:69], v[80:81] op_sel_hi:[1,0]
	v_pk_mul_f32 v[90:91], v[78:79], v[80:81] op_sel_hi:[1,0]
	v_pk_mul_f32 v[78:79], v[70:71], v[80:81] op_sel_hi:[1,0]
	v_pk_mul_f32 v[76:77], v[66:67], v[80:81] op_sel_hi:[1,0]
	v_mov_b32_e32 v66, v93
	v_mov_b32_e32 v67, v83
	v_pk_mul_f32 v[74:75], v[74:75], v[80:81] op_sel_hi:[1,0]
	v_pk_mul_f32 v[72:73], v[72:73], v[80:81] op_sel_hi:[1,0]
	v_pk_mul_f32 v[80:81], v[64:65], v[80:81] op_sel_hi:[1,0]
	v_mov_b32_e32 v64, v92
	v_mov_b32_e32 v65, v82
	v_pk_mul_f32 v[66:67], v[66:67], v[66:67]
	v_mov_b32_e32 v68, v91
	v_mov_b32_e32 v69, v79
	v_pk_fma_f32 v[64:65], v[64:65], v[64:65], v[66:67]
	v_mov_b32_e32 v66, v90
	v_mov_b32_e32 v67, v78
	v_pk_mul_f32 v[68:69], v[68:69], v[68:69]
	v_mov_b32_e32 v70, v75
	v_pk_fma_f32 v[66:67], v[66:67], v[66:67], v[68:69]
	v_mov_b32_e32 v68, v73
	v_mov_b32_e32 v69, v81
	v_pk_add_f32 v[64:65], v[64:65], v[66:67]
	v_mov_b32_e32 v66, v72
	v_mov_b32_e32 v67, v80
	v_pk_mul_f32 v[68:69], v[68:69], v[68:69]
	v_mov_b32_e32 v71, v77
	v_pk_fma_f32 v[66:67], v[66:67], v[66:67], v[68:69]
	v_mov_b32_e32 v68, v74
	v_mov_b32_e32 v69, v76
	v_pk_mul_f32 v[70:71], v[70:71], v[70:71]
	s_nop 0
	v_pk_fma_f32 v[68:69], v[68:69], v[68:69], v[70:71]
	s_nop 0
	v_pk_add_f32 v[66:67], v[66:67], v[68:69]
	s_nop 0
	v_pk_add_f32 v[64:65], v[64:65], v[66:67]
	s_nop 0
	v_add_f32_e32 v64, v64, v65
	ds_bpermute_b32 v65, v135, v64
	s_waitcnt lgkmcnt(0)
	v_add_f32_e32 v64, v64, v65
	ds_bpermute_b32 v65, v155, v64
	s_waitcnt lgkmcnt(0)
	v_add_f32_e32 v64, v64, v65
	v_fmamk_f32 v64, v64, 0x3c800000, v218
	v_cmp_gt_f32_e32 vcc, s3, v64
	v_mul_f32_e32 v65, 0x4f800000, v64
	s_nop 0
	v_cndmask_b32_e32 v64, v64, v65, vcc
	v_sqrt_f32_e32 v65, v64
	s_nop 0
	v_add_u32_e32 v66, -1, v65
	v_fma_f32 v67, -v66, v65, v64
	v_cmp_ge_f32_e64 s[0:1], 0, v67
	v_add_u32_e32 v67, 1, v65
	s_nop 0
	v_cndmask_b32_e64 v66, v65, v66, s[0:1]
	v_fma_f32 v65, -v67, v65, v64
	v_cmp_lt_f32_e64 s[0:1], 0, v65
	s_nop 1
	v_cndmask_b32_e64 v65, v66, v67, s[0:1]
	v_mul_f32_e32 v66, 0x37800000, v65
	v_cndmask_b32_e32 v65, v65, v66, vcc
	v_cmp_class_f32_e32 vcc, v64, v219
	s_nop 1
	v_cndmask_b32_e32 v64, v65, v64, vcc
	v_div_scale_f32 v65, s[0:1], v64, v64, 1.0
	v_rcp_f32_e32 v66, v65
	s_nop 0
	v_fma_f32 v67, -v65, v66, 1.0
	v_fmac_f32_e32 v66, v67, v66
	v_div_scale_f32 v67, vcc, 1.0, v64, 1.0
	v_mul_f32_e32 v68, v67, v66
	v_fma_f32 v69, -v65, v68, v67
	v_fmac_f32_e32 v68, v69, v66
	v_fma_f32 v65, -v65, v68, v67
	v_div_fmas_f32 v65, v65, v66, v68
	v_div_fixup_f32 v84, v65, v64, 1.0
	v_lshlrev_b64 v[64:65], 9, v[86:87]
	v_lshl_add_u64 v[88:89], s[14:15], 0, v[64:65]
	v_lshlrev_b64 v[64:65], 10, v[86:87]
	v_lshl_add_u64 v[86:87], s[24:25], 0, v[64:65]
	ds_read_b128 v[64:67], v132 offset:16
	ds_read_b128 v[68:71], v132
	v_pk_mul_f32 v[92:93], v[92:93], v[84:85] op_sel_hi:[1,0]
	v_pk_mul_f32 v[90:91], v[90:91], v[84:85] op_sel_hi:[1,0]
	v_pk_mul_f32 v[72:73], v[72:73], v[84:85] op_sel_hi:[1,0]
	v_pk_mul_f32 v[74:75], v[74:75], v[84:85] op_sel_hi:[1,0]
	v_lshl_add_u64 v[88:89], v[88:89], 0, v[124:125]
	v_lshl_add_u64 v[86:87], v[86:87], 0, v[184:185]
	s_waitcnt lgkmcnt(1)
	v_pk_mul_f32 v[66:67], v[66:67], v[74:75]
	s_waitcnt lgkmcnt(0)
	v_pk_mul_f32 v[70:71], v[70:71], v[90:91]
	v_pk_mul_f32 v[68:69], v[68:69], v[92:93]
	v_pk_mul_f32 v[64:65], v[64:65], v[72:73]
	v_cvt_pk_bf16_f32 v72, v68, v69
	v_cvt_pk_bf16_f32 v73, v70, v71
	s_nop 0
	v_cvt_pk_bf16_f32 v74, v64, v65
	v_cvt_pk_bf16_f32 v75, v66, v67
	global_store_dwordx4 v[88:89], v[72:75], off
	global_store_dwordx4 v[86:87], v[68:71], off nt
	global_store_dwordx4 v[86:87], v[64:67], off offset:16 nt
	ds_read_b128 v[64:67], v132 offset:144
	s_nop 0
	ds_read_b128 v[68:71], v132 offset:128
	v_pk_mul_f32 v[72:73], v[82:83], v[84:85] op_sel_hi:[1,0]
	v_pk_mul_f32 v[74:75], v[78:79], v[84:85] op_sel_hi:[1,0]
	s_waitcnt lgkmcnt(0)
; __device__ __forceinline__ float quad_sum(float s) { s += __shfl_xor(s, 16); s += __shfl_xor(s, 32); return s; }
; __device__ __forceinline__ float sq4(const f32x4 a) { return (a[0] * a[0] + a[1] * a[1]) + (a[2] * a[2] + a[3] * a[3]); }
; __device__ __forceinline__ u32x4 pack8(const f32x4 a, const f32x4 b) { u32x4 w; w.x = cvt_pk_bf16(a[0], a[1]); w.y = cvt_pk_bf16(a[2], a[3]); w.z = cvt_pk_bf16(b[0], b[1]); w.w = cvt_pk_bf16(b[2], b[3]); return w; }
;     __device__ __forceinline__ void operator()(const f32x4 (&acc)[2][2][4][2], const Unit& u, int wr, int wc, int fr, int fq) const {
;     ...
;                     int mrow = ai * HALF + wr * 64 + m * 16 + fr;
;                     asm volatile("" : "+v"(mrow));
;                     const float rs = MRS[b * 256 + mrow];
;                     f32x4 v[2][2];
; #pragma unroll
;                     for (int bj = 0; bj < 2; ++bj)
; #pragma unroll
;                         for (int n = 0; n < 2; ++n) v[bj][n] = acc[ai][bj][m][n] * rs;
;                     float ss = (sq4(v[0][0]) + sq4(v[0][1])) + (sq4(v[1][0]) + sq4(v[1][1]));
;                     ss = quad_sum(ss);
;                     const float hr = 1.0f / sqrtf(ss * (1.0f / 64.0f) + E_EPS);
; #pragma unroll
;                     for (int bj = 0; bj < 2; ++bj) {
;                         const int c0 = bj * 32 + 8 * fq;
;                         const f32x4 g0 = *(const f32x4*)(g + c0), g1 = *(const f32x4*)(g + c0 + 4);
;                         const f32x4 o0 = v[bj][0] * hr * g0, o1 = v[bj][1] * hr * g1;
;                         *(u32x4*)(MK + ((size_t)(l * 40 + b) * 256 + mrow) * 256 + wc * 64 + c0) = pack8(o0, o1);
;                         float* d = o_mk + ((size_t)(l * 8 + b) * 256 + mrow) * 256 + wc * 64 + c0; __builtin_nontemporal_store(o0, (f32x4*)d); __builtin_nontemporal_store(o1, (f32x4*)(d + 4));
;                     }
	v_pk_mul_f32 v[68:69], v[68:69], v[72:73]
	v_pk_mul_f32 v[70:71], v[70:71], v[74:75]
	v_pk_mul_f32 v[72:73], v[80:81], v[84:85] op_sel_hi:[1,0]
	v_pk_mul_f32 v[74:75], v[76:77], v[84:85] op_sel_hi:[1,0]
	v_pk_mul_f32 v[64:65], v[64:65], v[72:73]
	v_pk_mul_f32 v[66:67], v[66:67], v[74:75]
	v_cvt_pk_bf16_f32 v72, v68, v69
	v_cvt_pk_bf16_f32 v73, v70, v71
	v_cvt_pk_bf16_f32 v74, v64, v65
	s_nop 0
	v_cvt_pk_bf16_f32 v75, v66, v67
	global_store_dwordx4 v[88:89], v[72:75], off offset:64
	global_store_dwordx4 v[86:87], v[68:71], off offset:128 nt
	global_store_dwordx4 v[86:87], v[64:67], off offset:144 nt
	s_nop 0
	v_mov_b32_e32 v70, v164
	s_nop 0
	v_mov_b32_e32 v64, v220
	v_ashrrev_i32_e32 v71, 31, v70
	v_pk_mul_f32 v[76:77], v[60:61], v[64:65] op_sel_hi:[1,0]
	v_pk_mul_f32 v[66:67], v[52:53], v[64:65] op_sel_hi:[1,0]
	v_pk_mul_f32 v[74:75], v[62:63], v[64:65] op_sel_hi:[1,0]
	v_pk_mul_f32 v[62:63], v[54:55], v[64:65] op_sel_hi:[1,0]
	v_pk_mul_f32 v[60:61], v[50:51], v[64:65] op_sel_hi:[1,0]
	v_mov_b32_e32 v50, v77
	v_mov_b32_e32 v51, v67
	v_pk_mul_f32 v[58:59], v[58:59], v[64:65] op_sel_hi:[1,0]
	v_pk_mul_f32 v[56:57], v[56:57], v[64:65] op_sel_hi:[1,0]
	v_pk_mul_f32 v[64:65], v[48:49], v[64:65] op_sel_hi:[1,0]
	v_mov_b32_e32 v48, v76
	v_mov_b32_e32 v49, v66
	v_pk_mul_f32 v[50:51], v[50:51], v[50:51]
	v_mov_b32_e32 v52, v75
	v_mov_b32_e32 v53, v63
	v_pk_fma_f32 v[48:49], v[48:49], v[48:49], v[50:51]
	v_mov_b32_e32 v50, v74
	v_mov_b32_e32 v51, v62
	v_pk_mul_f32 v[52:53], v[52:53], v[52:53]
	v_mov_b32_e32 v54, v59
	v_pk_fma_f32 v[50:51], v[50:51], v[50:51], v[52:53]
	v_mov_b32_e32 v52, v57
	v_mov_b32_e32 v53, v65
	v_pk_add_f32 v[48:49], v[48:49], v[50:51]
	v_mov_b32_e32 v50, v56
	v_mov_b32_e32 v51, v64
	v_pk_mul_f32 v[52:53], v[52:53], v[52:53]
	v_mov_b32_e32 v55, v61
	v_pk_fma_f32 v[50:51], v[50:51], v[50:51], v[52:53]
	v_mov_b32_e32 v52, v58
	v_mov_b32_e32 v53, v60
	v_pk_mul_f32 v[54:55], v[54:55], v[54:55]
	s_nop 0
	v_pk_fma_f32 v[52:53], v[52:53], v[52:53], v[54:55]
	s_nop 0
	v_pk_add_f32 v[50:51], v[50:51], v[52:53]
	s_nop 0
	v_pk_add_f32 v[48:49], v[48:49], v[50:51]
	s_nop 0
	v_add_f32_e32 v48, v48, v49
	ds_bpermute_b32 v49, v135, v48
	s_waitcnt lgkmcnt(0)
	v_add_f32_e32 v48, v48, v49
	ds_bpermute_b32 v49, v155, v48
	s_waitcnt lgkmcnt(0)
	v_add_f32_e32 v48, v48, v49
	v_fmamk_f32 v48, v48, 0x3c800000, v218
	v_cmp_gt_f32_e32 vcc, s3, v48
	v_mul_f32_e32 v49, 0x4f800000, v48
	s_nop 0
	v_cndmask_b32_e32 v48, v48, v49, vcc
	v_sqrt_f32_e32 v49, v48
	s_nop 0
	v_add_u32_e32 v50, -1, v49
	v_fma_f32 v51, -v50, v49, v48
	v_cmp_ge_f32_e64 s[0:1], 0, v51
	v_add_u32_e32 v51, 1, v49
	s_nop 0
	v_cndmask_b32_e64 v50, v49, v50, s[0:1]
	v_fma_f32 v49, -v51, v49, v48
	v_cmp_lt_f32_e64 s[0:1], 0, v49
	s_nop 1
	v_cndmask_b32_e64 v49, v50, v51, s[0:1]
	v_mul_f32_e32 v50, 0x37800000, v49
	v_cndmask_b32_e32 v49, v49, v50, vcc
	v_cmp_class_f32_e32 vcc, v48, v219
	s_nop 1
	v_cndmask_b32_e32 v48, v49, v48, vcc
	v_div_scale_f32 v49, s[0:1], v48, v48, 1.0
	v_rcp_f32_e32 v50, v49
	s_nop 0
	v_fma_f32 v51, -v49, v50, 1.0
	v_fmac_f32_e32 v50, v51, v50
	v_div_scale_f32 v51, vcc, 1.0, v48, 1.0
	v_mul_f32_e32 v52, v51, v50
	v_fma_f32 v53, -v49, v52, v51
	v_fmac_f32_e32 v52, v53, v50
	v_fma_f32 v49, -v49, v52, v51
	v_div_fmas_f32 v49, v49, v50, v52
	v_div_fixup_f32 v68, v49, v48, 1.0
	v_lshlrev_b64 v[48:49], 9, v[70:71]
	v_lshl_add_u64 v[72:73], s[14:15], 0, v[48:49]
	v_lshlrev_b64 v[48:49], 10, v[70:71]
	v_lshl_add_u64 v[70:71], s[24:25], 0, v[48:49]
	ds_read_b128 v[48:51], v132 offset:16
	ds_read_b128 v[52:55], v132
	v_pk_mul_f32 v[76:77], v[76:77], v[68:69] op_sel_hi:[1,0]
	v_pk_mul_f32 v[74:75], v[74:75], v[68:69] op_sel_hi:[1,0]
	v_pk_mul_f32 v[56:57], v[56:57], v[68:69] op_sel_hi:[1,0]
	v_pk_mul_f32 v[58:59], v[58:59], v[68:69] op_sel_hi:[1,0]
	v_lshl_add_u64 v[72:73], v[72:73], 0, v[124:125]
	v_lshl_add_u64 v[70:71], v[70:71], 0, v[184:185]
	s_waitcnt lgkmcnt(1)
	v_pk_mul_f32 v[50:51], v[50:51], v[58:59]
	s_waitcnt lgkmcnt(0)
	v_pk_mul_f32 v[54:55], v[54:55], v[74:75]
	v_pk_mul_f32 v[52:53], v[52:53], v[76:77]
	v_pk_mul_f32 v[48:49], v[48:49], v[56:57]
	v_cvt_pk_bf16_f32 v56, v52, v53
	v_cvt_pk_bf16_f32 v57, v54, v55
	s_nop 0
	v_cvt_pk_bf16_f32 v58, v48, v49
	v_cvt_pk_bf16_f32 v59, v50, v51
	global_store_dwordx4 v[72:73], v[56:59], off
	global_store_dwordx4 v[70:71], v[52:55], off nt
	global_store_dwordx4 v[70:71], v[48:51], off offset:16 nt
	ds_read_b128 v[48:51], v132 offset:144
	s_nop 0
	ds_read_b128 v[52:55], v132 offset:128
	v_pk_mul_f32 v[56:57], v[66:67], v[68:69] op_sel_hi:[1,0]
	v_pk_mul_f32 v[58:59], v[62:63], v[68:69] op_sel_hi:[1,0]
	s_waitcnt lgkmcnt(0)
; __device__ __forceinline__ float quad_sum(float s) { s += __shfl_xor(s, 16); s += __shfl_xor(s, 32); return s; }
; __device__ __forceinline__ float sq4(const f32x4 a) { return (a[0] * a[0] + a[1] * a[1]) + (a[2] * a[2] + a[3] * a[3]); }
; __device__ __forceinline__ u32x4 pack8(const f32x4 a, const f32x4 b) { u32x4 w; w.x = cvt_pk_bf16(a[0], a[1]); w.y = cvt_pk_bf16(a[2], a[3]); w.z = cvt_pk_bf16(b[0], b[1]); w.w = cvt_pk_bf16(b[2], b[3]); return w; }
;     __device__ __forceinline__ void operator()(const f32x4 (&acc)[2][2][4][2], const Unit& u, int wr, int wc, int fr, int fq) const {
;     ...
;                     int mrow = ai * HALF + wr * 64 + m * 16 + fr;
;                     asm volatile("" : "+v"(mrow));
;                     const float rs = MRS[b * 256 + mrow];
;                     f32x4 v[2][2];
; #pragma unroll
;                     for (int bj = 0; bj < 2; ++bj)
; #pragma unroll
;                         for (int n = 0; n < 2; ++n) v[bj][n] = acc[ai][bj][m][n] * rs;
;                     float ss = (sq4(v[0][0]) + sq4(v[0][1])) + (sq4(v[1][0]) + sq4(v[1][1]));
;                     ss = quad_sum(ss);
;                     const float hr = 1.0f / sqrtf(ss * (1.0f / 64.0f) + E_EPS);
; #pragma unroll
;                     for (int bj = 0; bj < 2; ++bj) {
;                         const int c0 = bj * 32 + 8 * fq;
;                         const f32x4 g0 = *(const f32x4*)(g + c0), g1 = *(const f32x4*)(g + c0 + 4);
;                         const f32x4 o0 = v[bj][0] * hr * g0, o1 = v[bj][1] * hr * g1;
;                         *(u32x4*)(MK + ((size_t)(l * 40 + b) * 256 + mrow) * 256 + wc * 64 + c0) = pack8(o0, o1);
;                         float* d = o_mk + ((size_t)(l * 8 + b) * 256 + mrow) * 256 + wc * 64 + c0; __builtin_nontemporal_store(o0, (f32x4*)d); __builtin_nontemporal_store(o1, (f32x4*)(d + 4));
;                     }
	v_pk_mul_f32 v[52:53], v[52:53], v[56:57]
	v_pk_mul_f32 v[54:55], v[54:55], v[58:59]
	v_pk_mul_f32 v[56:57], v[64:65], v[68:69] op_sel_hi:[1,0]
	v_pk_mul_f32 v[58:59], v[60:61], v[68:69] op_sel_hi:[1,0]
	v_pk_mul_f32 v[48:49], v[48:49], v[56:57]
	v_pk_mul_f32 v[50:51], v[50:51], v[58:59]
	v_cvt_pk_bf16_f32 v56, v52, v53
	v_cvt_pk_bf16_f32 v57, v54, v55
	v_cvt_pk_bf16_f32 v58, v48, v49
	s_nop 0
	v_cvt_pk_bf16_f32 v59, v50, v51
	global_store_dwordx4 v[72:73], v[56:59], off offset:64
	global_store_dwordx4 v[70:71], v[52:55], off offset:128 nt
	global_store_dwordx4 v[70:71], v[48:51], off offset:144 nt
	s_nop 0
	v_mov_b32_e32 v54, v165
	s_nop 0
	v_mov_b32_e32 v48, v223
	v_ashrrev_i32_e32 v55, 31, v54
	v_pk_mul_f32 v[60:61], v[44:45], v[48:49] op_sel_hi:[1,0]
	v_pk_mul_f32 v[50:51], v[36:37], v[48:49] op_sel_hi:[1,0]
	v_pk_mul_f32 v[58:59], v[46:47], v[48:49] op_sel_hi:[1,0]
	v_pk_mul_f32 v[46:47], v[38:39], v[48:49] op_sel_hi:[1,0]
	v_pk_mul_f32 v[44:45], v[34:35], v[48:49] op_sel_hi:[1,0]
	v_mov_b32_e32 v34, v61
	v_mov_b32_e32 v35, v51
	v_pk_mul_f32 v[42:43], v[42:43], v[48:49] op_sel_hi:[1,0]
	v_pk_mul_f32 v[40:41], v[40:41], v[48:49] op_sel_hi:[1,0]
	v_pk_mul_f32 v[48:49], v[32:33], v[48:49] op_sel_hi:[1,0]
	v_mov_b32_e32 v32, v60
	v_mov_b32_e32 v33, v50
	v_pk_mul_f32 v[34:35], v[34:35], v[34:35]
	v_mov_b32_e32 v36, v59
	v_mov_b32_e32 v37, v47
	v_pk_fma_f32 v[32:33], v[32:33], v[32:33], v[34:35]
	v_mov_b32_e32 v34, v58
	v_mov_b32_e32 v35, v46
	v_pk_mul_f32 v[36:37], v[36:37], v[36:37]
	v_mov_b32_e32 v38, v43
	v_pk_fma_f32 v[34:35], v[34:35], v[34:35], v[36:37]
	v_mov_b32_e32 v36, v41
	v_mov_b32_e32 v37, v49
	v_pk_add_f32 v[32:33], v[32:33], v[34:35]
	v_mov_b32_e32 v34, v40
	v_mov_b32_e32 v35, v48
	v_pk_mul_f32 v[36:37], v[36:37], v[36:37]
	v_mov_b32_e32 v39, v45
	v_pk_fma_f32 v[34:35], v[34:35], v[34:35], v[36:37]
	v_mov_b32_e32 v36, v42
	v_mov_b32_e32 v37, v44
	v_pk_mul_f32 v[38:39], v[38:39], v[38:39]
	s_nop 0
	v_pk_fma_f32 v[36:37], v[36:37], v[36:37], v[38:39]
	s_nop 0
	v_pk_add_f32 v[34:35], v[34:35], v[36:37]
	s_nop 0
	v_pk_add_f32 v[32:33], v[32:33], v[34:35]
	s_nop 0
	v_add_f32_e32 v32, v32, v33
	ds_bpermute_b32 v33, v135, v32
	s_waitcnt lgkmcnt(0)
	v_add_f32_e32 v32, v32, v33
	ds_bpermute_b32 v33, v155, v32
	s_waitcnt lgkmcnt(0)
	v_add_f32_e32 v32, v32, v33
	v_fmamk_f32 v32, v32, 0x3c800000, v218
	v_cmp_gt_f32_e32 vcc, s3, v32
	v_mul_f32_e32 v33, 0x4f800000, v32
	s_nop 0
	v_cndmask_b32_e32 v32, v32, v33, vcc
	v_sqrt_f32_e32 v33, v32
	s_nop 0
	v_add_u32_e32 v34, -1, v33
	v_fma_f32 v35, -v34, v33, v32
	v_cmp_ge_f32_e64 s[0:1], 0, v35
	v_add_u32_e32 v35, 1, v33
	s_nop 0
	v_cndmask_b32_e64 v34, v33, v34, s[0:1]
	v_fma_f32 v33, -v35, v33, v32
	v_cmp_lt_f32_e64 s[0:1], 0, v33
	s_nop 1
	v_cndmask_b32_e64 v33, v34, v35, s[0:1]
	v_mul_f32_e32 v34, 0x37800000, v33
	v_cndmask_b32_e32 v33, v33, v34, vcc
	v_cmp_class_f32_e32 vcc, v32, v219
	s_nop 1
	v_cndmask_b32_e32 v32, v33, v32, vcc
	v_div_scale_f32 v33, s[0:1], v32, v32, 1.0
	v_rcp_f32_e32 v34, v33
	s_nop 0
	v_fma_f32 v35, -v33, v34, 1.0
	v_fmac_f32_e32 v34, v35, v34
	v_div_scale_f32 v35, vcc, 1.0, v32, 1.0
	v_mul_f32_e32 v36, v35, v34
	v_fma_f32 v37, -v33, v36, v35
	v_fmac_f32_e32 v36, v37, v34
	v_fma_f32 v33, -v33, v36, v35
	v_div_fmas_f32 v33, v33, v34, v36
	v_div_fixup_f32 v52, v33, v32, 1.0
	v_lshlrev_b64 v[32:33], 9, v[54:55]
	v_lshl_add_u64 v[56:57], s[14:15], 0, v[32:33]
	v_lshlrev_b64 v[32:33], 10, v[54:55]
	v_lshl_add_u64 v[54:55], s[24:25], 0, v[32:33]
	ds_read_b128 v[32:35], v132 offset:16
	ds_read_b128 v[36:39], v132
	v_pk_mul_f32 v[60:61], v[60:61], v[52:53] op_sel_hi:[1,0]
	v_pk_mul_f32 v[58:59], v[58:59], v[52:53] op_sel_hi:[1,0]
	v_pk_mul_f32 v[40:41], v[40:41], v[52:53] op_sel_hi:[1,0]
	v_pk_mul_f32 v[42:43], v[42:43], v[52:53] op_sel_hi:[1,0]
	v_lshl_add_u64 v[56:57], v[56:57], 0, v[124:125]
	v_lshl_add_u64 v[54:55], v[54:55], 0, v[184:185]
	s_waitcnt lgkmcnt(1)
	v_pk_mul_f32 v[34:35], v[34:35], v[42:43]
	s_waitcnt lgkmcnt(0)
	v_pk_mul_f32 v[38:39], v[38:39], v[58:59]
	v_pk_mul_f32 v[36:37], v[36:37], v[60:61]
	v_pk_mul_f32 v[32:33], v[32:33], v[40:41]
	v_cvt_pk_bf16_f32 v40, v36, v37
	v_cvt_pk_bf16_f32 v41, v38, v39
	s_nop 0
	v_cvt_pk_bf16_f32 v42, v32, v33
	v_cvt_pk_bf16_f32 v43, v34, v35
	global_store_dwordx4 v[56:57], v[40:43], off
	global_store_dwordx4 v[54:55], v[36:39], off nt
	global_store_dwordx4 v[54:55], v[32:35], off offset:16 nt
	ds_read_b128 v[32:35], v132 offset:144
	s_nop 0
	ds_read_b128 v[36:39], v132 offset:128
	v_pk_mul_f32 v[40:41], v[50:51], v[52:53] op_sel_hi:[1,0]
	v_pk_mul_f32 v[42:43], v[46:47], v[52:53] op_sel_hi:[1,0]
	s_waitcnt lgkmcnt(0)
; __device__ __forceinline__ float quad_sum(float s) { s += __shfl_xor(s, 16); s += __shfl_xor(s, 32); return s; }
; __device__ __forceinline__ float sq4(const f32x4 a) { return (a[0] * a[0] + a[1] * a[1]) + (a[2] * a[2] + a[3] * a[3]); }
; __device__ __forceinline__ u32x4 pack8(const f32x4 a, const f32x4 b) { u32x4 w; w.x = cvt_pk_bf16(a[0], a[1]); w.y = cvt_pk_bf16(a[2], a[3]); w.z = cvt_pk_bf16(b[0], b[1]); w.w = cvt_pk_bf16(b[2], b[3]); return w; }
;     __device__ __forceinline__ void operator()(const f32x4 (&acc)[2][2][4][2], const Unit& u, int wr, int wc, int fr, int fq) const {
;     ...
;                     int mrow = ai * HALF + wr * 64 + m * 16 + fr;
;                     asm volatile("" : "+v"(mrow));
;                     const float rs = MRS[b * 256 + mrow];
;                     f32x4 v[2][2];
; #pragma unroll
;                     for (int bj = 0; bj < 2; ++bj)
; #pragma unroll
;                         for (int n = 0; n < 2; ++n) v[bj][n] = acc[ai][bj][m][n] * rs;
;                     float ss = (sq4(v[0][0]) + sq4(v[0][1])) + (sq4(v[1][0]) + sq4(v[1][1]));
;                     ss = quad_sum(ss);
;                     const float hr = 1.0f / sqrtf(ss * (1.0f / 64.0f) + E_EPS);
; #pragma unroll
;                     for (int bj = 0; bj < 2; ++bj) {
;                         const int c0 = bj * 32 + 8 * fq;
;                         const f32x4 g0 = *(const f32x4*)(g + c0), g1 = *(const f32x4*)(g + c0 + 4);
;                         const f32x4 o0 = v[bj][0] * hr * g0, o1 = v[bj][1] * hr * g1;
;                         *(u32x4*)(MK + ((size_t)(l * 40 + b) * 256 + mrow) * 256 + wc * 64 + c0) = pack8(o0, o1);
;                         float* d = o_mk + ((size_t)(l * 8 + b) * 256 + mrow) * 256 + wc * 64 + c0; __builtin_nontemporal_store(o0, (f32x4*)d); __builtin_nontemporal_store(o1, (f32x4*)(d + 4));
;                     }
	v_pk_mul_f32 v[36:37], v[36:37], v[40:41]
	v_pk_mul_f32 v[38:39], v[38:39], v[42:43]
	v_pk_mul_f32 v[40:41], v[48:49], v[52:53] op_sel_hi:[1,0]
	v_pk_mul_f32 v[42:43], v[44:45], v[52:53] op_sel_hi:[1,0]
	v_pk_mul_f32 v[32:33], v[32:33], v[40:41]
	v_pk_mul_f32 v[34:35], v[34:35], v[42:43]
	v_cvt_pk_bf16_f32 v40, v36, v37
	v_cvt_pk_bf16_f32 v41, v38, v39
	v_cvt_pk_bf16_f32 v42, v32, v33
	s_nop 0
	v_cvt_pk_bf16_f32 v43, v34, v35
	global_store_dwordx4 v[56:57], v[40:43], off offset:64
	global_store_dwordx4 v[54:55], v[36:39], off offset:128 nt
	global_store_dwordx4 v[54:55], v[32:35], off offset:144 nt
	s_nop 0
	v_mov_b32_e32 v38, v166
	s_nop 0
	v_mov_b32_e32 v32, v226
	v_ashrrev_i32_e32 v39, 31, v38
	v_pk_mul_f32 v[44:45], v[28:29], v[32:33] op_sel_hi:[1,0]
	v_pk_mul_f32 v[34:35], v[20:21], v[32:33] op_sel_hi:[1,0]
	v_pk_mul_f32 v[42:43], v[30:31], v[32:33] op_sel_hi:[1,0]
	v_pk_mul_f32 v[30:31], v[22:23], v[32:33] op_sel_hi:[1,0]
	v_pk_mul_f32 v[28:29], v[18:19], v[32:33] op_sel_hi:[1,0]
	v_mov_b32_e32 v18, v45
	v_mov_b32_e32 v19, v35
	v_pk_mul_f32 v[26:27], v[26:27], v[32:33] op_sel_hi:[1,0]
	v_pk_mul_f32 v[24:25], v[24:25], v[32:33] op_sel_hi:[1,0]
	v_pk_mul_f32 v[32:33], v[16:17], v[32:33] op_sel_hi:[1,0]
	v_mov_b32_e32 v16, v44
	v_mov_b32_e32 v17, v34
	v_pk_mul_f32 v[18:19], v[18:19], v[18:19]
	v_mov_b32_e32 v20, v43
	v_mov_b32_e32 v21, v31
	v_pk_fma_f32 v[16:17], v[16:17], v[16:17], v[18:19]
	v_mov_b32_e32 v18, v42
	v_mov_b32_e32 v19, v30
	v_pk_mul_f32 v[20:21], v[20:21], v[20:21]
	v_mov_b32_e32 v22, v27
	v_pk_fma_f32 v[18:19], v[18:19], v[18:19], v[20:21]
	v_mov_b32_e32 v20, v25
	v_mov_b32_e32 v21, v33
	v_pk_add_f32 v[16:17], v[16:17], v[18:19]
	v_mov_b32_e32 v18, v24
	v_mov_b32_e32 v19, v32
	v_pk_mul_f32 v[20:21], v[20:21], v[20:21]
	v_mov_b32_e32 v23, v29
	v_pk_fma_f32 v[18:19], v[18:19], v[18:19], v[20:21]
	v_mov_b32_e32 v20, v26
	v_mov_b32_e32 v21, v28
	v_pk_mul_f32 v[22:23], v[22:23], v[22:23]
	s_nop 0
	v_pk_fma_f32 v[20:21], v[20:21], v[20:21], v[22:23]
	s_nop 0
	v_pk_add_f32 v[18:19], v[18:19], v[20:21]
	s_nop 0
	v_pk_add_f32 v[16:17], v[16:17], v[18:19]
	s_nop 0
	v_add_f32_e32 v16, v16, v17
	ds_bpermute_b32 v17, v135, v16
	s_waitcnt lgkmcnt(0)
	v_add_f32_e32 v16, v16, v17
	ds_bpermute_b32 v17, v155, v16
	s_waitcnt lgkmcnt(0)
	v_add_f32_e32 v16, v16, v17
	v_fmamk_f32 v16, v16, 0x3c800000, v218
	v_cmp_gt_f32_e32 vcc, s3, v16
	v_mul_f32_e32 v17, 0x4f800000, v16
	s_nop 0
	v_cndmask_b32_e32 v16, v16, v17, vcc
	v_sqrt_f32_e32 v17, v16
	s_nop 0
	v_add_u32_e32 v18, -1, v17
	v_fma_f32 v19, -v18, v17, v16
	v_cmp_ge_f32_e64 s[0:1], 0, v19
	v_add_u32_e32 v19, 1, v17
	s_nop 0
	v_cndmask_b32_e64 v18, v17, v18, s[0:1]
	v_fma_f32 v17, -v19, v17, v16
	v_cmp_lt_f32_e64 s[0:1], 0, v17
	s_nop 1
	v_cndmask_b32_e64 v17, v18, v19, s[0:1]
	v_mul_f32_e32 v18, 0x37800000, v17
	v_cndmask_b32_e32 v17, v17, v18, vcc
	v_cmp_class_f32_e32 vcc, v16, v219
	s_nop 1
	v_cndmask_b32_e32 v16, v17, v16, vcc
	v_div_scale_f32 v17, s[0:1], v16, v16, 1.0
	v_rcp_f32_e32 v18, v17
	s_nop 0
	v_fma_f32 v19, -v17, v18, 1.0
	v_fmac_f32_e32 v18, v19, v18
	v_div_scale_f32 v19, vcc, 1.0, v16, 1.0
	v_mul_f32_e32 v20, v19, v18
	v_fma_f32 v21, -v17, v20, v19
	v_fmac_f32_e32 v20, v21, v18
	v_fma_f32 v17, -v17, v20, v19
	v_div_fmas_f32 v17, v17, v18, v20
	v_div_fixup_f32 v36, v17, v16, 1.0
	v_lshlrev_b64 v[16:17], 9, v[38:39]
	v_lshl_add_u64 v[40:41], s[14:15], 0, v[16:17]
	v_lshlrev_b64 v[16:17], 10, v[38:39]
	v_lshl_add_u64 v[38:39], s[24:25], 0, v[16:17]
	ds_read_b128 v[16:19], v132 offset:16
	ds_read_b128 v[20:23], v132
	v_pk_mul_f32 v[44:45], v[44:45], v[36:37] op_sel_hi:[1,0]
	v_pk_mul_f32 v[42:43], v[42:43], v[36:37] op_sel_hi:[1,0]
	v_pk_mul_f32 v[24:25], v[24:25], v[36:37] op_sel_hi:[1,0]
	v_pk_mul_f32 v[26:27], v[26:27], v[36:37] op_sel_hi:[1,0]
	v_lshl_add_u64 v[40:41], v[40:41], 0, v[124:125]
	v_lshl_add_u64 v[38:39], v[38:39], 0, v[184:185]
	s_waitcnt lgkmcnt(1)
	v_pk_mul_f32 v[18:19], v[18:19], v[26:27]
	s_waitcnt lgkmcnt(0)
	v_pk_mul_f32 v[22:23], v[22:23], v[42:43]
	v_pk_mul_f32 v[20:21], v[20:21], v[44:45]
	v_pk_mul_f32 v[16:17], v[16:17], v[24:25]
	v_cvt_pk_bf16_f32 v24, v20, v21
	v_cvt_pk_bf16_f32 v25, v22, v23
	s_nop 0
	v_cvt_pk_bf16_f32 v26, v16, v17
	v_cvt_pk_bf16_f32 v27, v18, v19
	global_store_dwordx4 v[40:41], v[24:27], off
	global_store_dwordx4 v[38:39], v[20:23], off nt
	global_store_dwordx4 v[38:39], v[16:19], off offset:16 nt
	ds_read_b128 v[16:19], v132 offset:144
	s_nop 0
	ds_read_b128 v[20:23], v132 offset:128
	v_pk_mul_f32 v[24:25], v[34:35], v[36:37] op_sel_hi:[1,0]
	v_pk_mul_f32 v[26:27], v[30:31], v[36:37] op_sel_hi:[1,0]
	s_waitcnt lgkmcnt(0)
; __device__ __forceinline__ float quad_sum(float s) { s += __shfl_xor(s, 16); s += __shfl_xor(s, 32); return s; }
; __device__ __forceinline__ float sq4(const f32x4 a) { return (a[0] * a[0] + a[1] * a[1]) + (a[2] * a[2] + a[3] * a[3]); }
; __device__ __forceinline__ u32x4 pack8(const f32x4 a, const f32x4 b) { u32x4 w; w.x = cvt_pk_bf16(a[0], a[1]); w.y = cvt_pk_bf16(a[2], a[3]); w.z = cvt_pk_bf16(b[0], b[1]); w.w = cvt_pk_bf16(b[2], b[3]); return w; }
;     __device__ __forceinline__ void operator()(const f32x4 (&acc)[2][2][4][2], const Unit& u, int wr, int wc, int fr, int fq) const {
;     ...
;                     int mrow = ai * HALF + wr * 64 + m * 16 + fr;
;                     asm volatile("" : "+v"(mrow));
;                     const float rs = MRS[b * 256 + mrow];
;                     f32x4 v[2][2];
; #pragma unroll
;                     for (int bj = 0; bj < 2; ++bj)
; #pragma unroll
;                         for (int n = 0; n < 2; ++n) v[bj][n] = acc[ai][bj][m][n] * rs;
;                     float ss = (sq4(v[0][0]) + sq4(v[0][1])) + (sq4(v[1][0]) + sq4(v[1][1]));
;                     ss = quad_sum(ss);
;                     const float hr = 1.0f / sqrtf(ss * (1.0f / 64.0f) + E_EPS);
; #pragma unroll
;                     for (int bj = 0; bj < 2; ++bj) {
;                         const int c0 = bj * 32 + 8 * fq;
;                         const f32x4 g0 = *(const f32x4*)(g + c0), g1 = *(const f32x4*)(g + c0 + 4);
;                         const f32x4 o0 = v[bj][0] * hr * g0, o1 = v[bj][1] * hr * g1;
;                         *(u32x4*)(MK + ((size_t)(l * 40 + b) * 256 + mrow) * 256 + wc * 64 + c0) = pack8(o0, o1);
;                         float* d = o_mk + ((size_t)(l * 8 + b) * 256 + mrow) * 256 + wc * 64 + c0; __builtin_nontemporal_store(o0, (f32x4*)d); __builtin_nontemporal_store(o1, (f32x4*)(d + 4));
;                     }
	v_pk_mul_f32 v[20:21], v[20:21], v[24:25]
	v_pk_mul_f32 v[22:23], v[22:23], v[26:27]
	v_pk_mul_f32 v[24:25], v[32:33], v[36:37] op_sel_hi:[1,0]
	v_pk_mul_f32 v[26:27], v[28:29], v[36:37] op_sel_hi:[1,0]
	v_pk_mul_f32 v[16:17], v[16:17], v[24:25]
	v_pk_mul_f32 v[18:19], v[18:19], v[26:27]
	v_cvt_pk_bf16_f32 v24, v20, v21
	v_cvt_pk_bf16_f32 v25, v22, v23
	v_cvt_pk_bf16_f32 v26, v16, v17
	s_nop 0
	v_cvt_pk_bf16_f32 v27, v18, v19
	global_store_dwordx4 v[40:41], v[24:27], off offset:64
	global_store_dwordx4 v[38:39], v[20:23], off offset:128 nt
	global_store_dwordx4 v[38:39], v[16:19], off offset:144 nt
	s_nop 0
	v_mov_b32_e32 v22, v167
	s_nop 0
	v_mov_b32_e32 v16, v250
	v_ashrrev_i32_e32 v23, 31, v22
	v_pk_mul_f32 v[28:29], v[12:13], v[16:17] op_sel_hi:[1,0]
	v_pk_mul_f32 v[18:19], v[4:5], v[16:17] op_sel_hi:[1,0]
	v_pk_mul_f32 v[26:27], v[14:15], v[16:17] op_sel_hi:[1,0]
	v_pk_mul_f32 v[14:15], v[6:7], v[16:17] op_sel_hi:[1,0]
	v_pk_mul_f32 v[12:13], v[2:3], v[16:17] op_sel_hi:[1,0]
	v_mov_b32_e32 v2, v29
	v_mov_b32_e32 v3, v19
	v_pk_mul_f32 v[10:11], v[10:11], v[16:17] op_sel_hi:[1,0]
	v_pk_mul_f32 v[8:9], v[8:9], v[16:17] op_sel_hi:[1,0]
	v_pk_mul_f32 v[16:17], v[0:1], v[16:17] op_sel_hi:[1,0]
	v_mov_b32_e32 v0, v28
	v_mov_b32_e32 v1, v18
	v_pk_mul_f32 v[2:3], v[2:3], v[2:3]
	v_mov_b32_e32 v4, v27
	v_mov_b32_e32 v5, v15
	v_pk_fma_f32 v[0:1], v[0:1], v[0:1], v[2:3]
	v_mov_b32_e32 v2, v26
	v_mov_b32_e32 v3, v14
	v_pk_mul_f32 v[4:5], v[4:5], v[4:5]
	v_mov_b32_e32 v6, v11
	v_pk_fma_f32 v[2:3], v[2:3], v[2:3], v[4:5]
	v_mov_b32_e32 v4, v9
	v_mov_b32_e32 v5, v17
	v_pk_add_f32 v[0:1], v[0:1], v[2:3]
	v_mov_b32_e32 v2, v8
	v_mov_b32_e32 v3, v16
	v_pk_mul_f32 v[4:5], v[4:5], v[4:5]
	v_mov_b32_e32 v7, v13
	v_pk_fma_f32 v[2:3], v[2:3], v[2:3], v[4:5]
	v_mov_b32_e32 v4, v10
	v_mov_b32_e32 v5, v12
	v_pk_mul_f32 v[6:7], v[6:7], v[6:7]
	s_nop 0
	v_pk_fma_f32 v[4:5], v[4:5], v[4:5], v[6:7]
	s_nop 0
	v_pk_add_f32 v[2:3], v[2:3], v[4:5]
	s_nop 0
	v_pk_add_f32 v[0:1], v[0:1], v[2:3]
	s_nop 0
	v_add_f32_e32 v0, v0, v1
	ds_bpermute_b32 v1, v135, v0
	s_waitcnt lgkmcnt(0)
	v_add_f32_e32 v0, v0, v1
	ds_bpermute_b32 v1, v155, v0
	s_waitcnt lgkmcnt(0)
	v_add_f32_e32 v0, v0, v1
	v_fmamk_f32 v0, v0, 0x3c800000, v218
	v_cmp_gt_f32_e32 vcc, s3, v0
	v_mul_f32_e32 v1, 0x4f800000, v0
	s_nop 0
	v_cndmask_b32_e32 v0, v0, v1, vcc
	v_sqrt_f32_e32 v1, v0
	s_nop 0
	v_add_u32_e32 v2, -1, v1
	v_fma_f32 v3, -v2, v1, v0
	v_cmp_ge_f32_e64 s[0:1], 0, v3
	v_add_u32_e32 v3, 1, v1
	s_nop 0
	v_cndmask_b32_e64 v2, v1, v2, s[0:1]
	v_fma_f32 v1, -v3, v1, v0
	v_cmp_lt_f32_e64 s[0:1], 0, v1
	s_nop 1
	v_cndmask_b32_e64 v1, v2, v3, s[0:1]
	v_mul_f32_e32 v2, 0x37800000, v1
	v_cndmask_b32_e32 v1, v1, v2, vcc
	v_cmp_class_f32_e32 vcc, v0, v219
	s_nop 1
	v_cndmask_b32_e32 v0, v1, v0, vcc
	v_div_scale_f32 v1, s[0:1], v0, v0, 1.0
	v_rcp_f32_e32 v2, v1
	s_nop 0
	v_fma_f32 v3, -v1, v2, 1.0
	v_fmac_f32_e32 v2, v3, v2
	v_div_scale_f32 v3, vcc, 1.0, v0, 1.0
	v_mul_f32_e32 v4, v3, v2
	v_fma_f32 v5, -v1, v4, v3
	v_fmac_f32_e32 v4, v5, v2
	v_fma_f32 v1, -v1, v4, v3
	v_div_fmas_f32 v1, v1, v2, v4
	v_div_fixup_f32 v20, v1, v0, 1.0
	v_lshlrev_b64 v[0:1], 9, v[22:23]
	v_lshl_add_u64 v[24:25], s[14:15], 0, v[0:1]
	v_lshlrev_b64 v[0:1], 10, v[22:23]
	v_lshl_add_u64 v[22:23], s[24:25], 0, v[0:1]
	ds_read_b128 v[0:3], v132 offset:16
	ds_read_b128 v[4:7], v132
	v_pk_mul_f32 v[28:29], v[28:29], v[20:21] op_sel_hi:[1,0]
	v_pk_mul_f32 v[26:27], v[26:27], v[20:21] op_sel_hi:[1,0]
	v_pk_mul_f32 v[8:9], v[8:9], v[20:21] op_sel_hi:[1,0]
	v_pk_mul_f32 v[10:11], v[10:11], v[20:21] op_sel_hi:[1,0]
	v_lshl_add_u64 v[24:25], v[24:25], 0, v[124:125]
	v_pk_mul_f32 v[14:15], v[14:15], v[20:21] op_sel_hi:[1,0]
	v_pk_mul_f32 v[12:13], v[12:13], v[20:21] op_sel_hi:[1,0]
	s_waitcnt lgkmcnt(1)
	v_pk_mul_f32 v[0:1], v[0:1], v[8:9]
	s_waitcnt lgkmcnt(0)
	v_pk_mul_f32 v[6:7], v[6:7], v[26:27]
	v_pk_mul_f32 v[4:5], v[4:5], v[28:29]
	v_pk_mul_f32 v[2:3], v[2:3], v[10:11]
	v_cvt_pk_bf16_f32 v8, v4, v5
	v_cvt_pk_bf16_f32 v9, v6, v7
	v_cvt_pk_bf16_f32 v10, v0, v1
	s_nop 0
	v_cvt_pk_bf16_f32 v11, v2, v3
	global_store_dwordx4 v[24:25], v[8:11], off
	s_nop 1
	v_lshl_add_u64 v[8:9], v[22:23], 0, v[184:185]
	global_store_dwordx4 v[8:9], v[4:7], off nt
	global_store_dwordx4 v[8:9], v[0:3], off offset:16 nt
	ds_read_b128 v[0:3], v132 offset:144
	s_nop 0
	ds_read_b128 v[4:7], v132 offset:128
	v_pk_mul_f32 v[10:11], v[18:19], v[20:21] op_sel_hi:[1,0]
	v_lshl_add_u64 v[156:157], v[8:9], 0, s[96:97]
	s_waitcnt lgkmcnt(1)
	v_pk_mul_f32 v[130:131], v[2:3], v[12:13]
	s_waitcnt lgkmcnt(0)
	v_pk_mul_f32 v[4:5], v[4:5], v[10:11]
	v_pk_mul_f32 v[10:11], v[16:17], v[20:21] op_sel_hi:[1,0]
	v_pk_mul_f32 v[6:7], v[6:7], v[14:15]
	v_pk_mul_f32 v[128:129], v[0:1], v[10:11]
	v_cvt_pk_bf16_f32 v0, v4, v5
	v_cvt_pk_bf16_f32 v1, v6, v7
	s_nop 0
	v_cvt_pk_bf16_f32 v2, v128, v129
	v_cvt_pk_bf16_f32 v3, v130, v131
	global_store_dwordx4 v[24:25], v[0:3], off offset:64
	global_store_dwordx4 v[8:9], v[4:7], off offset:128 nt
	s_andn2_b64 vcc, exec, s[36:37]
	s_mov_b64 s[0:1], -1
	global_store_dwordx4 v[156:157], v[128:131], off offset:16 nt
	s_cbranch_vccnz .LBB0_501

; #define PG8_STAGE(bufoff, gbase, voff) do { _Pragma("unroll") for (int _i = 0; _i < 2; ++_i) \
;         __builtin_amdgcn_global_load_lds((const unsigned*)((const char*)(gbase) + (voff)[_i]), (PG8_LAS unsigned*)(lds + (bufoff) + ldsw + _i * 8192), 16, 0, 0); } while (0)
; #define PG8_LDA(dst, b, h) do { _Pragma("unroll") for (int m = 0; m < 4; ++m) _Pragma("unroll") for (int k = 0; k < 2; ++k) dst[m][k] = *(const PG8_LAS bf16x8*)(lds + PG8_SA(b, h) + aoff + m * 2048 + k * 1024); } while (0)
; #define PG8_LDB(dst, b, h) do { _Pragma("unroll") for (int n = 0; n < 2; ++n) _Pragma("unroll") for (int k = 0; k < 2; ++k) dst[n][k] = *(const PG8_LAS bf16x8*)(lds + PG8_SB(b, h) + boff + n * 2048 + k * 1024); } while (0)
; #define PG8_MMA(ai, bj, At, Bt) do { __builtin_amdgcn_s_setprio(1); _Pragma("unroll") for (int m = 0; m < 4; ++m) _Pragma("unroll") for (int n = 0; n < 2; ++n) _Pragma("unroll") for (int k = 0; k < 2; ++k) \
;         acc[ai][bj][m][n] = __builtin_amdgcn_mfma_f32_16x16x32_bf16(Bt[n][k], At[m][k], acc[ai][bj][m][n], 0, 0, 0); __builtin_amdgcn_s_setprio(0); } while (0)
; #define PG8_WAIT_V(n) asm volatile("s_waitcnt vmcnt(" #n ")" ::: "memory")
; #define PG8_WAIT_L(n) asm volatile("s_waitcnt lgkmcnt(" #n ")" ::: "memory")
; #define PG8_BAR __builtin_amdgcn_s_barrier()
; #define PG8_SCHED __builtin_amdgcn_sched_barrier(0)
; template <class Epi, class Sched, bool ALIGN_EPI = false, bool SP2 = false>
; __device__ __forceinline__ void gemm_phase(PG8_LAS unsigned char* lds, const Gemm g, const Sched& S, const Epi& E) {
;     ...
;             PG8_LDB(B0, 0, 0); PG8_LDB(B1, 0, 1); PG8_SCHED; PG8_LDA(At, 0, 0); PG8_STAGE(PG8_SA(1, 1), a1 + hstep, voffA);
;             PG8_WAIT_V(8); PG8_WAIT_L(0); PG8_BAR; PG8_MMA(0, 0, At, B0); PG8_MMA(0, 1, At, B1); PG8_BAR; PG8_SCHED;
;             PG8_LDA(At, 0, 1); PG8_STAGE(PG8_SB(0, 0), b2, voffB); PG8_STAGE(PG8_SB(0, 1), b2 + hstep, voffB); PG8_STAGE(PG8_SA(0, 0), a2, voffA);
;             PG8_WAIT_V(8); PG8_WAIT_L(0); PG8_BAR; PG8_MMA(1, 0, At, B0); PG8_MMA(1, 1, At, B1); PG8_BAR; PG8_SCHED;
.Lrs_in_a:
	s_add_i32 s54, 0, 0x14000
	v_add_u32_e32 v140, s39, v155
	v_add_u32_e32 v184, s54, v155
	ds_read_b128 v[128:131], v140
	ds_read_b128 v[132:135], v140 offset:1024
	ds_read_b128 v[136:139], v140 offset:2048
	ds_read_b128 v[140:143], v140 offset:3072
	ds_read_b128 v[170:173], v184
	ds_read_b128 v[174:177], v184 offset:1024
	ds_read_b128 v[180:183], v184 offset:2048
	ds_read_b128 v[194:197], v184 offset:3072
	v_lshl_add_u64 v[214:215], s[0:1], 0, v[166:167]
	s_add_i32 m0, s23, 0xc000
	ds_read_b128 v[198:201], v179
	ds_read_b128 v[202:205], v179 offset:1024
	ds_read_b128 v[206:209], v179 offset:2048
	ds_read_b128 v[210:213], v179 offset:3072
	ds_read_b128 v[228:231], v179 offset:4096
	ds_read_b128 v[232:235], v179 offset:5120
	ds_read_b128 v[236:239], v179 offset:6144
	ds_read_b128 v[240:243], v179 offset:7168
	global_load_lds_dwordx4 v[214:215], off
	v_lshl_add_u64 v[214:215], s[0:1], 0, v[168:169]
	s_add_i32 m0, s23, 0xe000
	s_nop 0
	global_load_lds_dwordx4 v[214:215], off
	s_nop 0
	s_nop 0
	s_waitcnt vmcnt(8)
	s_waitcnt lgkmcnt(0)
	s_barrier
	s_setprio 1
	s_waitcnt lgkmcnt(0)
	v_mfma_f32_16x16x32_bf16 v[124:127], v[128:131], v[198:201], v[124:127]
	v_mfma_f32_16x16x32_bf16 v[120:123], v[136:139], v[198:201], v[120:123]
	v_mfma_f32_16x16x32_bf16 v[108:111], v[128:131], v[206:209], v[108:111]
	v_mfma_f32_16x16x32_bf16 v[104:107], v[136:139], v[206:209], v[104:107]
	v_mfma_f32_16x16x32_bf16 v[92:95], v[128:131], v[228:231], v[92:95]
	v_mfma_f32_16x16x32_bf16 v[88:91], v[136:139], v[228:231], v[88:91]
	v_mfma_f32_16x16x32_bf16 v[76:79], v[128:131], v[236:239], v[76:79]
	v_mfma_f32_16x16x32_bf16 v[72:75], v[136:139], v[236:239], v[72:75]
	v_mfma_f32_16x16x32_bf16 v[124:127], v[132:135], v[202:205], v[124:127]
	v_mfma_f32_16x16x32_bf16 v[120:123], v[140:143], v[202:205], v[120:123]
	v_mfma_f32_16x16x32_bf16 v[108:111], v[132:135], v[210:213], v[108:111]
	v_mfma_f32_16x16x32_bf16 v[104:107], v[140:143], v[210:213], v[104:107]
	v_mfma_f32_16x16x32_bf16 v[92:95], v[132:135], v[232:235], v[92:95]
	v_mfma_f32_16x16x32_bf16 v[88:91], v[140:143], v[232:235], v[88:91]
	v_mfma_f32_16x16x32_bf16 v[76:79], v[132:135], v[240:243], v[76:79]
	v_mfma_f32_16x16x32_bf16 v[72:75], v[140:143], v[240:243], v[72:75]
	s_setprio 0
	s_setprio 1
	v_mfma_f32_16x16x32_bf16 v[116:119], v[170:173], v[198:201], v[116:119]
	v_mfma_f32_16x16x32_bf16 v[112:115], v[180:183], v[198:201], v[112:115]
	v_mfma_f32_16x16x32_bf16 v[100:103], v[170:173], v[206:209], v[100:103]
	v_mfma_f32_16x16x32_bf16 v[96:99], v[180:183], v[206:209], v[96:99]
	v_mfma_f32_16x16x32_bf16 v[84:87], v[170:173], v[228:231], v[84:87]
	v_mfma_f32_16x16x32_bf16 v[80:83], v[180:183], v[228:231], v[80:83]
	v_mfma_f32_16x16x32_bf16 v[68:71], v[170:173], v[236:239], v[68:71]
	v_mfma_f32_16x16x32_bf16 v[64:67], v[180:183], v[236:239], v[64:67]
	v_mfma_f32_16x16x32_bf16 v[116:119], v[174:177], v[202:205], v[116:119]
	v_mfma_f32_16x16x32_bf16 v[112:115], v[194:197], v[202:205], v[112:115]
	v_mfma_f32_16x16x32_bf16 v[100:103], v[174:177], v[210:213], v[100:103]
	v_mfma_f32_16x16x32_bf16 v[96:99], v[194:197], v[210:213], v[96:99]
	v_mfma_f32_16x16x32_bf16 v[84:87], v[174:177], v[232:235], v[84:87]
	v_mfma_f32_16x16x32_bf16 v[80:83], v[194:197], v[232:235], v[80:83]
	v_mfma_f32_16x16x32_bf16 v[68:71], v[174:177], v[240:243], v[68:71]
	v_mfma_f32_16x16x32_bf16 v[64:67], v[194:197], v[240:243], v[64:67]
	s_setprio 0
	s_barrier
	s_add_i32 s39, s39, s22
	v_lshl_add_u64 v[214:215], s[2:3], 0, v[148:149]
	s_mov_b32 m0, s39
	ds_read_b128 v[198:201], v179 offset:16384
	ds_read_b128 v[202:205], v179 offset:17408
	ds_read_b128 v[206:209], v179 offset:18432
	ds_read_b128 v[210:213], v179 offset:19456
	ds_read_b128 v[228:231], v179 offset:20480
	ds_read_b128 v[232:235], v179 offset:21504
	ds_read_b128 v[236:239], v179 offset:22528
	ds_read_b128 v[240:243], v179 offset:23552
	global_load_lds_dwordx4 v[214:215], off
	s_add_i32 m0, s39, 0x2000
	s_add_u32 s40, s2, 0x40000
	v_lshl_add_u64 v[224:225], s[2:3], 0, v[144:145]
	s_addc_u32 s41, s3, 0
	s_add_i32 s39, s54, s22
	global_load_lds_dwordx4 v[224:225], off
	v_lshl_add_u64 v[244:245], s[40:41], 0, v[148:149]
	s_mov_b32 m0, s39
	v_lshl_add_u64 v[246:247], s[24:25], 0, v[146:147]
	global_load_lds_dwordx4 v[244:245], off
	v_lshl_add_u64 v[244:245], s[40:41], 0, v[144:145]
	s_add_i32 m0, s39, 0x2000
	s_nop 0
	global_load_lds_dwordx4 v[244:245], off
	v_lshl_add_u64 v[244:245], s[24:25], 0, v[150:151]
	s_mov_b32 m0, s23
	s_nop 0
	global_load_lds_dwordx4 v[244:245], off
	s_mov_b32 m0, s44
	s_nop 0
	global_load_lds_dwordx4 v[246:247], off
	s_nop 0
	s_waitcnt vmcnt(8)
	s_waitcnt lgkmcnt(0)
	s_barrier
; #define PG8_LAS __attribute__((address_space(3)))
; __device__ __forceinline__ unsigned cvt_pk_bf16(float lo, float hi) { unsigned r; asm volatile("v_cvt_pk_bf16_f32 %0, %1, %2" : "=v"(r) : "v"(lo), "v"(hi)); return r; }
; __device__ __forceinline__ float sum4(const f32x4 a) { return (a[0] + a[1]) + (a[2] + a[3]); }
; #define PG8_BAR __builtin_amdgcn_s_barrier()
; __device__ __forceinline__ float row_rstd(const float* ps_row) {
;     const f32x4* p = (const f32x4*)ps_row; const f32x4 a = p[0], b = p[1], c = p[2], d = p[3];
;     const float s = (sum4(a) + sum4(b)) + (sum4(c) + sum4(d));
;     return 1.0f / sqrtf(s * (1.0f / 1024.0f) + E_EPS);
; }
; __device__ __forceinline__ u32x4 pack8(const f32x4 a, const f32x4 b) { u32x4 w; w.x = cvt_pk_bf16(a[0], a[1]); w.y = cvt_pk_bf16(a[2], a[3]); w.z = cvt_pk_bf16(b[0], b[1]); w.w = cvt_pk_bf16(b[2], b[3]); return w; }
; __device__ __forceinline__ bf16_t f2bf1(float f) { return (bf16_t)(cvt_pk_bf16(f, 0.f) & 0xffffu); }
; __device__ __forceinline__ PG8_LAS const float* stage_rstd(const float* PS, PG8_LAS unsigned char* lds, int pm) {
;     int t = threadIdx.x; asm volatile("" : "+v"(t));
;     PG8_LAS float* R = (PG8_LAS float*)(lds + 131072);
;     if (t < 256) R[t] = row_rstd(PS + (size_t)(pm * BM + t) * 16);
; template <class Epi, class Sched, bool ALIGN_EPI = false, bool SP2 = false>
; __device__ __forceinline__ void gemm_phase(PG8_LAS unsigned char* lds, const Gemm g, const Sched& S, const Epi& E) {
;     ...
;             PG8_WAIT_V(8); PG8_WAIT_L(0); PG8_BAR; PG8_MMA(0, 0, At, B0); PG8_MMA(0, 1, At, B1); PG8_BAR; PG8_SCHED;
;             PG8_LDA(At, 0, 1); PG8_STAGE(PG8_SB(0, 0), b2, voffB); PG8_STAGE(PG8_SB(0, 1), b2 + hstep, voffB); PG8_STAGE(PG8_SA(0, 0), a2, voffA);
;             PG8_WAIT_V(8); PG8_WAIT_L(0); PG8_BAR; PG8_MMA(1, 0, At, B0); PG8_MMA(1, 1, At, B1); PG8_BAR; PG8_SCHED;
;             PG8_LDB(B0, 1, 0); PG8_LDB(B1, 1, 1); PG8_SCHED; PG8_LDA(At, 1, 0); PG8_STAGE(PG8_SA(0, 1), a2 + hstep, voffA);
;             PG8_WAIT_V(8); PG8_WAIT_L(0); PG8_BAR; PG8_MMA(0, 0, At, B0); PG8_MMA(0, 1, At, B1); PG8_BAR; PG8_SCHED;
;             PG8_LDA(At, 1, 1); PG8_STAGE(PG8_SB(1, 0), b3, voffB); PG8_STAGE(PG8_SB(1, 1), b3 + hstep, voffB); PG8_STAGE(PG8_SA(1, 0), a3, voffA);
;             PG8_WAIT_V(8); PG8_WAIT_L(0); PG8_BAR; PG8_MMA(1, 0, At, B0); PG8_MMA(1, 1, At, B1); PG8_BAR; PG8_SCHED;
	s_setprio 1
	s_waitcnt lgkmcnt(0)
	v_mfma_f32_16x16x32_bf16 v[60:63], v[128:131], v[198:201], v[60:63]
	v_mfma_f32_16x16x32_bf16 v[56:59], v[136:139], v[198:201], v[56:59]
	v_mfma_f32_16x16x32_bf16 v[44:47], v[128:131], v[206:209], v[44:47]
	v_mfma_f32_16x16x32_bf16 v[40:43], v[136:139], v[206:209], v[40:43]
	v_mfma_f32_16x16x32_bf16 v[28:31], v[128:131], v[228:231], v[28:31]
	v_mfma_f32_16x16x32_bf16 v[24:27], v[136:139], v[228:231], v[24:27]
	v_mfma_f32_16x16x32_bf16 v[12:15], v[128:131], v[236:239], v[12:15]
	v_mfma_f32_16x16x32_bf16 v[8:11], v[136:139], v[236:239], v[8:11]
	v_mfma_f32_16x16x32_bf16 v[60:63], v[132:135], v[202:205], v[60:63]
	v_mfma_f32_16x16x32_bf16 v[56:59], v[140:143], v[202:205], v[56:59]
	v_mfma_f32_16x16x32_bf16 v[44:47], v[132:135], v[210:213], v[44:47]
	v_mfma_f32_16x16x32_bf16 v[40:43], v[140:143], v[210:213], v[40:43]
	v_mfma_f32_16x16x32_bf16 v[28:31], v[132:135], v[232:235], v[28:31]
	v_mfma_f32_16x16x32_bf16 v[24:27], v[140:143], v[232:235], v[24:27]
	v_mfma_f32_16x16x32_bf16 v[12:15], v[132:135], v[240:243], v[12:15]
	v_mfma_f32_16x16x32_bf16 v[8:11], v[140:143], v[240:243], v[8:11]
	s_setprio 0
	s_setprio 1
	v_mfma_f32_16x16x32_bf16 v[52:55], v[170:173], v[198:201], v[52:55]
	v_mfma_f32_16x16x32_bf16 v[48:51], v[180:183], v[198:201], v[48:51]
	v_mfma_f32_16x16x32_bf16 v[36:39], v[170:173], v[206:209], v[36:39]
	v_mfma_f32_16x16x32_bf16 v[32:35], v[180:183], v[206:209], v[32:35]
	v_mfma_f32_16x16x32_bf16 v[20:23], v[170:173], v[228:231], v[20:23]
	v_mfma_f32_16x16x32_bf16 v[16:19], v[180:183], v[228:231], v[16:19]
	v_mfma_f32_16x16x32_bf16 v[4:7], v[170:173], v[236:239], v[4:7]
	v_mfma_f32_16x16x32_bf16 v[0:3], v[180:183], v[236:239], v[0:3]
	v_mfma_f32_16x16x32_bf16 v[52:55], v[174:177], v[202:205], v[52:55]
	v_mfma_f32_16x16x32_bf16 v[48:51], v[194:197], v[202:205], v[48:51]
	v_mfma_f32_16x16x32_bf16 v[36:39], v[174:177], v[210:213], v[36:39]
	v_mfma_f32_16x16x32_bf16 v[32:35], v[194:197], v[210:213], v[32:35]
	v_mfma_f32_16x16x32_bf16 v[20:23], v[174:177], v[232:235], v[20:23]
	v_mfma_f32_16x16x32_bf16 v[16:19], v[194:197], v[232:235], v[16:19]
	v_mfma_f32_16x16x32_bf16 v[4:7], v[174:177], v[240:243], v[4:7]
	v_mfma_f32_16x16x32_bf16 v[0:3], v[194:197], v[240:243], v[0:3]
	s_setprio 0
	s_barrier
	s_add_i32 s39, 0, 0x18000
	s_add_i32 s40, 0, 0x1c000
	s_cmp_eq_u32 s38, 12
	s_cbranch_scc0 .Lrs_in_b
	v_add_f32_e32 v190, v190, v191
	v_add_f32_e32 v226, v226, v227
	v_add_f32_e32 v217, v217, v220
	v_add_f32_e32 v223, v223, v250
	v_add_f32_e32 v190, v190, v226
	v_add_f32_e32 v217, v217, v223
	v_add_f32_e32 v190, v190, v217
	s_nop 1
	v_add_f32_dpp v190, v190, v190 quad_perm:[1,0,3,2] row_mask:0xf bank_mask:0xf
	s_mov_b32 s98, 0xf800000
	v_fmamk_f32 v190, v190, 0x3a800000, v218
	v_mul_f32_e32 v191, 0x4f800000, v190
	v_cmp_gt_f32_e32 vcc, s98, v190
	s_nop 1
	v_cndmask_b32_e32 v190, v190, v191, vcc
	v_sqrt_f32_e32 v191, v190
	s_nop 0
	v_add_u32_e32 v217, -1, v191
	v_add_u32_e32 v220, 1, v191
	v_fma_f32 v223, -v217, v191, v190
	v_fma_f32 v226, -v220, v191, v190
	v_cmp_ge_f32_e64 s[98:99], 0, v223
	s_nop 1
	v_cndmask_b32_e64 v191, v191, v217, s[98:99]
	v_cmp_lt_f32_e64 s[98:99], 0, v226
	s_nop 1
	v_cndmask_b32_e64 v191, v191, v220, s[98:99]
	v_mul_f32_e32 v217, 0x37800000, v191
	v_cndmask_b32_e32 v191, v191, v217, vcc
	v_cmp_class_f32_e32 vcc, v190, v219
	s_nop 1
	v_cndmask_b32_e32 v190, v191, v190, vcc
	v_div_scale_f32 v191, s[98:99], v190, v190, 1.0
	v_rcp_f32_e32 v217, v191
	v_div_scale_f32 v220, vcc, 1.0, v190, 1.0
	v_fma_f32 v223, -v191, v217, 1.0
	v_fmac_f32_e32 v217, v223, v217
	v_mul_f32_e32 v223, v220, v217
	v_fma_f32 v226, -v191, v223, v220
	v_fmac_f32_e32 v223, v226, v217
	v_fma_f32 v191, -v191, v223, v220
	v_div_fmas_f32 v191, v191, v217, v223
	v_div_fixup_f32 v190, v191, v190, 1.0
	v_lshrrev_b32_e32 v250, 1, v216
	v_lshl_add_u32 v250, v250, 2, 0
	v_add_u32_e32 v250, 0x20000, v250
	ds_write_b32 v250, v190
